# rowop kinds 1/2: wave_sum butterflies (6 ds_bpermute round trips each) replaced by DPP row adds + v_permlane16/32_swap
# speedup vs baseline: 1.0087x; 1.0013x over previous
.LBB0_28:
	s_movk_i32 s0, 0x4000
	v_cmp_gt_i32_e32 vcc, s0, v104
	s_or_b64 s[0:1], s[6:7], vcc
	s_and_saveexec_b64 s[8:9], s[0:1]
	s_cbranch_execz .LBB0_27
	s_movk_i32 s0, 0x4000
	v_cmp_gt_i32_e32 vcc, s0, v104
	v_min_i32_e32 v0, 0x4000, v104
	v_ashrrev_i32_e32 v1, 31, v104
	v_readlane_b32 s0, v253, 42
	v_ashrrev_i32_e32 v172, 13, v0
	v_add_u32_e32 v0, 0xffffc000, v104
	v_cndmask_b32_e32 v105, 0, v1, vcc
	v_mov_b32_e32 v2, s0
	v_mov_b32_e32 v3, s89
	v_readlane_b32 s0, v255, 17
	v_cndmask_b32_e32 v0, v0, v104, vcc
	v_mov_b32_e32 v1, v105
	v_cndmask_b32_e32 v3, v2, v3, vcc
	v_mov_b32_e32 v2, s0
	v_mov_b32_e32 v4, s88
	v_cndmask_b32_e32 v2, v2, v4, vcc
	v_lshlrev_b64 v[0:1], 12, v[0:1]
	v_lshl_add_u64 v[120:121], v[2:3], 0, v[0:1]
	v_add_u32_e32 v0, s10, v172
	v_mul_hi_i32_i24_e32 v33, 0x6000, v0
	v_mul_i32_i24_e32 v32, 0x6000, v0
	v_lshl_add_u64 v[0:1], v[120:121], 0, v[192:193]
	s_movk_i32 s12, 0x1000
	v_add_co_u32_e32 v2, vcc, s12, v0
	s_movk_i32 s13, 0x2000
	s_nop 0
	v_addc_co_u32_e32 v3, vcc, 0, v1, vcc
	v_add_co_u32_e32 v4, vcc, s13, v0
	global_load_dwordx4 v[92:95], v[0:1], off nt
	global_load_dwordx4 v[88:91], v[0:1], off offset:1024 nt
	global_load_dwordx4 v[84:87], v[0:1], off offset:2048 nt
	global_load_dwordx4 v[80:83], v[0:1], off offset:3072 nt
	v_addc_co_u32_e32 v5, vcc, 0, v1, vcc
	v_add_co_u32_e32 v0, vcc, s73, v0
	global_load_dwordx4 v[76:79], v[4:5], off offset:-4096 nt
	global_load_dwordx4 v[72:75], v[2:3], off offset:1024 nt
	global_load_dwordx4 v[68:71], v[2:3], off offset:2048 nt
	global_load_dwordx4 v[64:67], v[2:3], off offset:3072 nt
	global_load_dwordx4 v[28:31], v[4:5], off nt
	global_load_dwordx4 v[24:27], v[4:5], off offset:1024 nt
	global_load_dwordx4 v[20:23], v[4:5], off offset:2048 nt
	global_load_dwordx4 v[16:19], v[4:5], off offset:3072 nt
	v_addc_co_u32_e32 v1, vcc, 0, v1, vcc
	global_load_dwordx4 v[12:15], v[0:1], off nt
	global_load_dwordx4 v[8:11], v[0:1], off offset:1024 nt
	global_load_dwordx4 v[4:7], v[0:1], off offset:2048 nt
	s_nop 0
	global_load_dwordx4 v[0:3], v[0:1], off offset:3072 nt
	v_add_u32_e32 v34, 1, v104
	v_ashrrev_i32_e32 v35, 31, v34
	v_lshlrev_b64 v[116:117], 11, v[34:35]
	v_add_u32_e32 v34, 2, v104
	v_ashrrev_i32_e32 v35, 31, v34
	v_lshlrev_b64 v[114:115], 11, v[34:35]
	v_add_u32_e32 v34, 3, v104
	v_ashrrev_i32_e32 v35, 31, v34
	v_cmp_lt_i32_e32 vcc, v211, v210
	v_lshlrev_b64 v[112:113], 11, v[34:35]
	v_lshl_add_u64 v[32:33], s[90:91], 0, v[32:33]
	v_cndmask_b32_e32 v34, v209, v211, vcc
	v_cmp_lt_i32_e32 vcc, v212, v210
	v_lshlrev_b32_e32 v107, 2, v34
	v_lshl_add_u64 v[36:37], v[32:33], 0, v[192:193]
	v_cndmask_b32_e32 v34, v209, v212, vcc
	v_cmp_lt_i32_e32 vcc, v206, v210
	v_lshlrev_b32_e32 v109, 2, v34
	s_mov_b64 s[0:1], 0x345d000
	v_cndmask_b32_e32 v34, v209, v206, vcc
	v_cmp_lt_i32_e32 vcc, v213, v210
	v_lshlrev_b32_e32 v111, 2, v34
	v_lshl_add_u64 v[62:63], v[36:37], 0, s[0:1]
	v_cndmask_b32_e32 v34, v209, v213, vcc
	v_cmp_lt_i32_e32 vcc, v216, v210
	v_lshlrev_b32_e32 v169, 2, v34
	s_mov_b32 s0, 0x345d000
	v_cndmask_b32_e32 v34, v209, v216, vcc
	v_cmp_lt_i32_e32 vcc, v217, v210
	v_lshlrev_b32_e32 v170, 2, v34
	v_lshlrev_b64 v[118:119], 11, v[104:105]
	v_cndmask_b32_e32 v34, v209, v217, vcc
	v_add_co_u32_e32 v36, vcc, s0, v36
	v_lshl_add_u64 v[60:61], v[96:97], 0, v[118:119]
	s_nop 0
	v_addc_co_u32_e32 v37, vcc, 0, v37, vcc
	v_lshlrev_b32_e32 v171, 2, v34
	global_load_dwordx4 v[32:35], v[98:99], off
	v_lshl_add_u64 v[140:141], v[96:97], 0, v[116:117]
	global_load_dwordx4 v[36:39], v[36:37], off
	s_nop 0
	global_load_dwordx4 v[40:43], v[98:99], off offset:1024
	global_load_dwordx4 v[44:47], v[62:63], off offset:1024
	global_load_dwordx4 v[48:51], v[98:99], off offset:2048
	global_load_dwordx4 v[52:55], v[62:63], off offset:2048
	s_mov_b32 s0, 0x358637bd
	s_mov_b32 s16, 0x3a800000
	s_mov_b32 s14, 0x800000
	v_lshl_add_u64 v[134:135], v[96:97], 0, v[114:115]
	v_lshl_add_u64 v[124:125], v[96:97], 0, v[112:113]
	s_waitcnt vmcnt(21)
	v_mov_b32_e32 v138, v92
	s_waitcnt vmcnt(17)
	v_mov_b32_e32 v136, v76
	s_waitcnt vmcnt(16)
	v_mov_b32_e32 v142, v72
	v_mov_b32_e32 v143, v74
	v_mov_b32_e32 v74, v73
	v_mov_b32_e32 v137, v78
	s_waitcnt vmcnt(12)
	v_mov_b32_e32 v72, v24
	v_mov_b32_e32 v73, v26
	v_mov_b32_e32 v26, v25
	v_mov_b32_e32 v24, v68
	v_mov_b32_e32 v25, v70
	v_mov_b32_e32 v70, v69
	s_waitcnt vmcnt(7)
	v_mov_b32_e32 v68, v4
	v_mov_b32_e32 v69, v6
	v_mov_b32_e32 v6, v5
	global_load_dwordx4 v[56:59], v[98:99], off offset:3072
	global_load_dwordx2 v[4:5], v[60:61], off offset:1536 nt
	global_load_dwordx2 v[180:181], v[60:61], off offset:1024 nt
	global_load_dwordx2 v[182:183], v[60:61], off offset:512 nt
	global_load_dwordx2 v[184:185], v[60:61], off nt
	global_load_dwordx2 v[186:187], v[140:141], off offset:1536 nt
	global_load_dwordx2 v[188:189], v[140:141], off offset:1024 nt
	global_load_dwordx2 v[190:191], v[140:141], off offset:512 nt
	global_load_dwordx2 v[224:225], v[140:141], off nt
	global_load_dwordx2 v[232:233], v[134:135], off offset:1536 nt
	global_load_dwordx2 v[234:235], v[134:135], off offset:1024 nt
	global_load_dwordx2 v[236:237], v[134:135], off offset:512 nt
	global_load_dwordx2 v[238:239], v[134:135], off nt
	global_load_dwordx2 v[240:241], v[124:125], off offset:1536 nt
	global_load_dwordx2 v[242:243], v[124:125], off offset:1024 nt
	global_load_dwordx2 v[248:249], v[124:125], off offset:512 nt
	global_load_dwordx2 v[250:251], v[124:125], off nt
	v_mov_b32_e32 v78, v77
	v_mov_b32_e32 v144, v84
	v_mov_b32_e32 v145, v86
	v_mov_b32_e32 v86, v85
	v_mov_b32_e32 v84, v20
	v_mov_b32_e32 v85, v22
	v_mov_b32_e32 v22, v21
	v_mov_b32_e32 v139, v94
	v_mov_b32_e32 v94, v93
	s_waitcnt vmcnt(22)
	v_mov_b32_e32 v130, v32
	v_mov_b32_e32 v131, v34
	s_waitcnt vmcnt(21)
	v_mov_b32_e32 v122, v36
	s_waitcnt vmcnt(19)
	v_mov_b32_e32 v76, v44
	v_mov_b32_e32 v77, v46
	v_mov_b32_e32 v46, v45
	v_mov_b32_e32 v44, v8
	v_mov_b32_e32 v45, v10
	v_mov_b32_e32 v10, v9
	s_waitcnt vmcnt(17)
	v_mov_b32_e32 v8, v52
	v_mov_b32_e32 v9, v54
	v_mov_b32_e32 v54, v53
	v_mov_b32_e32 v123, v38
	v_mov_b32_e32 v38, v37
	v_mov_b32_e32 v36, v28
	v_mov_b32_e32 v37, v30
	v_mov_b32_e32 v30, v29
	v_mov_b32_e32 v28, v12
	v_mov_b32_e32 v29, v14
	v_mov_b32_e32 v14, v13
	v_mov_b32_e32 v12, v88
	v_mov_b32_e32 v13, v90
	v_mov_b32_e32 v90, v89
	v_mov_b32_e32 v34, v33
	v_mov_b32_e32 v32, v80
	v_mov_b32_e32 v33, v82
	v_mov_b32_e32 v82, v81
	s_waitcnt vmcnt(15)
	v_and_b32_e32 v21, 0xffff0000, v5
	v_and_b32_e32 v20, 0xffff0000, v4
	v_lshlrev_b32_e32 v52, 16, v4
	v_lshlrev_b32_e32 v53, 16, v5
	v_mov_b32_e32 v93, v52
	v_mov_b32_e32 v127, v53
	v_mov_b32_e32 v89, v21
	s_waitcnt vmcnt(14)
	v_mov_b32_e32 v4, v180
	v_mov_b32_e32 v5, v181
	v_and_b32_e32 v146, 0xffff0000, v4
	v_and_b32_e32 v147, 0xffff0000, v5
	v_lshlrev_b32_e32 v148, 16, v4
	v_lshlrev_b32_e32 v149, 16, v5
	v_mov_b32_e32 v4, v146
	v_mov_b32_e32 v5, v20
	v_pk_mul_f32 v[4:5], v[4:5], v[4:5]
	v_mov_b32_e32 v92, v148
	v_mov_b32_e32 v126, v149
	v_pk_fma_f32 v[4:5], v[92:93], v[92:93], v[4:5]
	v_mov_b32_e32 v88, v147
	v_pk_fma_f32 v[4:5], v[126:127], v[126:127], v[4:5]
	s_nop 0
	v_pk_fma_f32 v[88:89], v[88:89], v[88:89], v[4:5]
	s_waitcnt vmcnt(13)
	v_mov_b32_e32 v4, v182
	v_mov_b32_e32 v5, v183
	v_and_b32_e32 v151, 0xffff0000, v5
	v_and_b32_e32 v150, 0xffff0000, v4
	v_lshlrev_b32_e32 v152, 16, v4
	v_lshlrev_b32_e32 v153, 16, v5
	v_mov_b32_e32 v127, v152
	v_mov_b32_e32 v129, v153
	v_mov_b32_e32 v61, v151
	s_waitcnt vmcnt(12)
	v_mov_b32_e32 v4, v184
	v_mov_b32_e32 v5, v185
	v_and_b32_e32 v92, 0xffff0000, v4
	v_and_b32_e32 v93, 0xffff0000, v5
	v_lshlrev_b32_e32 v154, 16, v4
	v_lshlrev_b32_e32 v155, 16, v5
	v_mov_b32_e32 v4, v92
	v_mov_b32_e32 v5, v150
	v_pk_mul_f32 v[4:5], v[4:5], v[4:5]
	v_mov_b32_e32 v126, v154
	v_mov_b32_e32 v128, v155
	v_pk_fma_f32 v[4:5], v[126:127], v[126:127], v[4:5]
	v_mov_b32_e32 v60, v93
	v_pk_fma_f32 v[4:5], v[128:129], v[128:129], v[4:5]
	v_mov_b32_e32 v128, v40
	v_mov_b32_e32 v129, v42
	v_mov_b32_e32 v42, v41
	v_pk_fma_f32 v[156:157], v[60:61], v[60:61], v[4:5]
	global_load_dwordx4 v[60:63], v[62:63], off offset:3072
	v_mov_b32_e32 v126, v48
	v_mov_b32_e32 v127, v50
	v_mov_b32_e32 v50, v49
	v_mov_b32_e32 v4, v56
	v_mov_b32_e32 v5, v58
	v_mov_b32_e32 v58, v57
	s_waitcnt vmcnt(12)
	v_mov_b32_e32 v40, v186
	v_mov_b32_e32 v41, v187
	v_and_b32_e32 v159, 0xffff0000, v41
	v_and_b32_e32 v158, 0xffff0000, v40
	v_lshlrev_b32_e32 v160, 16, v40
	v_lshlrev_b32_e32 v161, 16, v41
	s_waitcnt vmcnt(0)
	v_mov_b32_e32 v132, v60
	v_mov_b32_e32 v133, v62
	v_mov_b32_e32 v62, v61
	v_mov_b32_e32 v61, v160
	v_mov_b32_e32 v81, v161
	v_mov_b32_e32 v57, v159
	s_waitcnt vmcnt(0)
	v_mov_b32_e32 v40, v188
	v_mov_b32_e32 v41, v189
	v_and_b32_e32 v48, 0xffff0000, v40
	v_and_b32_e32 v49, 0xffff0000, v41
	v_lshlrev_b32_e32 v162, 16, v40
	v_lshlrev_b32_e32 v163, 16, v41
	v_mov_b32_e32 v40, v48
	v_mov_b32_e32 v41, v158
	v_pk_mul_f32 v[40:41], v[40:41], v[40:41]
	v_mov_b32_e32 v60, v162
	v_mov_b32_e32 v80, v163
	v_pk_fma_f32 v[40:41], v[60:61], v[60:61], v[40:41]
	v_mov_b32_e32 v56, v49
	v_pk_fma_f32 v[40:41], v[80:81], v[80:81], v[40:41]
	s_nop 0
	v_pk_fma_f32 v[40:41], v[56:57], v[56:57], v[40:41]
	s_waitcnt vmcnt(0)
	v_mov_b32_e32 v56, v190
	v_mov_b32_e32 v57, v191
	v_and_b32_e32 v165, 0xffff0000, v57
	v_and_b32_e32 v164, 0xffff0000, v56
	v_lshlrev_b32_e32 v166, 16, v56
	v_lshlrev_b32_e32 v167, 16, v57
	v_mov_b32_e32 v81, v166
	v_mov_b32_e32 v141, v167
	v_mov_b32_e32 v61, v165
	s_waitcnt vmcnt(0)
	v_mov_b32_e32 v56, v224
	v_mov_b32_e32 v57, v225
	v_and_b32_e32 v174, 0xffff0000, v56
	v_and_b32_e32 v175, 0xffff0000, v57
	v_lshlrev_b32_e32 v176, 16, v56
	v_lshlrev_b32_e32 v177, 16, v57
	v_mov_b32_e32 v56, v174
	v_mov_b32_e32 v57, v164
	v_pk_mul_f32 v[56:57], v[56:57], v[56:57]
	v_mov_b32_e32 v80, v176
	v_mov_b32_e32 v140, v177
	v_pk_fma_f32 v[56:57], v[80:81], v[80:81], v[56:57]
	v_mov_b32_e32 v60, v175
	v_pk_fma_f32 v[56:57], v[140:141], v[140:141], v[56:57]
	v_mov_b64_e32 v[140:141], s[0:1]
	v_pk_fma_f32 v[56:57], v[60:61], v[60:61], v[56:57]
	v_mov_b32_e32 v61, v156
	v_mov_b32_e32 v60, v56
	v_mov_b32_e32 v156, v57
	v_pk_add_f32 v[56:57], v[60:61], v[156:157]
	v_mov_b32_e32 v60, v40
	v_mov_b32_e32 v61, v88
	v_pk_add_f32 v[56:57], v[56:57], v[60:61]
	v_mov_b32_e32 v88, v41
	v_pk_add_f32 v[40:41], v[56:57], v[88:89]
	s_nop 0
	s_nop 1
	v_add_f32_dpp v41, v41, v41 quad_perm:[1,0,3,2] row_mask:0xf bank_mask:0xf
	v_add_f32_dpp v40, v40, v40 quad_perm:[1,0,3,2] row_mask:0xf bank_mask:0xf
	s_nop 0
	v_add_f32_dpp v41, v41, v41 quad_perm:[2,3,0,1] row_mask:0xf bank_mask:0xf
	v_add_f32_dpp v40, v40, v40 quad_perm:[2,3,0,1] row_mask:0xf bank_mask:0xf
	s_nop 0
	v_add_f32_dpp v41, v41, v41 row_half_mirror row_mask:0xf bank_mask:0xf
	v_add_f32_dpp v40, v40, v40 row_half_mirror row_mask:0xf bank_mask:0xf
	s_nop 0
	v_add_f32_dpp v41, v41, v41 row_mirror row_mask:0xf bank_mask:0xf
	v_add_f32_dpp v40, v40, v40 row_mirror row_mask:0xf bank_mask:0xf
	s_nop 0
	v_mov_b32_e32 v57, v41
	v_mov_b32_e32 v56, v40
	s_nop 0
	v_permlane16_swap_b32_e32 v41, v57
	v_permlane16_swap_b32_e32 v40, v56
	s_nop 0
	v_add_f32_e32 v41, v41, v57
	v_add_f32_e32 v40, v40, v56
	s_nop 0
	v_mov_b32_e32 v57, v41
	v_mov_b32_e32 v56, v40
	s_nop 0
	v_permlane32_swap_b32_e32 v41, v57
	v_permlane32_swap_b32_e32 v40, v56
	s_nop 0
	v_add_f32_e32 v41, v41, v57
	v_add_f32_e32 v40, v40, v56
	s_nop 0
	s_nop 0
	v_pk_fma_f32 v[156:157], v[40:41], s[16:17], v[140:141] op_sel_hi:[1,0,0]
	s_nop 0
	v_mul_f32_e32 v40, 0x4b800000, v157
	v_cmp_gt_f32_e64 s[0:1], s14, v157
	v_cmp_gt_f32_e32 vcc, s14, v156
	s_nop 0
	v_cndmask_b32_e64 v40, v157, v40, s[0:1]
	v_rsq_f32_e32 v40, v40
	s_nop 0
	v_mul_f32_e32 v41, 0x45800000, v40
	v_cndmask_b32_e64 v178, v40, v41, s[0:1]
	v_pk_mul_f32 v[40:41], v[178:179], v[154:155] op_sel_hi:[0,1]
	v_pk_mul_f32 v[40:41], v[40:41], v[130:131]
	v_pk_mul_f32 v[56:57], v[178:179], v[92:93] op_sel_hi:[0,1]
	v_pk_fma_f32 v[92:93], v[40:41], v[122:123], v[138:139]
	v_pk_mul_f32 v[40:41], v[178:179], v[152:153] op_sel_hi:[0,1]
	v_pk_mul_f32 v[56:57], v[56:57], v[34:35]
	v_pk_mul_f32 v[40:41], v[40:41], v[128:129]
	v_pk_fma_f32 v[88:89], v[56:57], v[38:39], v[94:95]
	v_pk_mul_f32 v[56:57], v[178:179], v[150:151] op_sel_hi:[0,1]
	v_pk_fma_f32 v[80:81], v[40:41], v[76:77], v[12:13]
	v_pk_mul_f32 v[12:13], v[178:179], v[148:149] op_sel_hi:[0,1]
	v_pk_mul_f32 v[56:57], v[56:57], v[42:43]
	v_pk_mul_f32 v[12:13], v[12:13], v[126:127]
	v_pk_fma_f32 v[60:61], v[56:57], v[46:47], v[90:91]
	v_pk_fma_f32 v[56:57], v[12:13], v[8:9], v[144:145]
	v_pk_mul_f32 v[12:13], v[178:179], v[52:53] op_sel_hi:[0,1]
	v_pk_mul_f32 v[20:21], v[178:179], v[20:21] op_sel_hi:[0,1]
	v_pk_mul_f32 v[12:13], v[12:13], v[4:5]
	v_pk_mul_f32 v[20:21], v[20:21], v[58:59]
	v_pk_fma_f32 v[32:33], v[12:13], v[132:133], v[32:33]
	v_pk_fma_f32 v[12:13], v[20:21], v[62:63], v[82:83]
	v_mul_f32_e32 v20, 0x4b800000, v156
	v_cndmask_b32_e32 v20, v156, v20, vcc
	v_rsq_f32_e32 v20, v20
	v_pk_mul_f32 v[40:41], v[178:179], v[146:147] op_sel_hi:[0,1]
	v_pk_mul_f32 v[40:41], v[40:41], v[50:51]
	v_mul_f32_e32 v21, 0x45800000, v20
	v_cndmask_b32_e32 v20, v20, v21, vcc
	v_pk_mul_f32 v[48:49], v[20:21], v[48:49] op_sel_hi:[0,1]
	v_pk_mul_f32 v[48:49], v[48:49], v[50:51]
	v_pk_mul_f32 v[82:83], v[20:21], v[174:175] op_sel_hi:[0,1]
	v_pk_fma_f32 v[48:49], v[48:49], v[54:55], v[70:71]
	v_mov_b32_e32 v70, v64
	v_mov_b32_e32 v71, v66
	v_mov_b32_e32 v66, v65
	v_pk_mul_f32 v[82:83], v[82:83], v[34:35]
	v_pk_mul_f32 v[52:53], v[20:21], v[176:177] op_sel_hi:[0,1]
	v_pk_fma_f32 v[82:83], v[82:83], v[38:39], v[78:79]
	v_pk_mul_f32 v[78:79], v[20:21], v[164:165] op_sel_hi:[0,1]
	v_pk_mul_f32 v[90:91], v[78:79], v[42:43]
	v_pk_mul_f32 v[52:53], v[52:53], v[130:131]
	v_pk_fma_f32 v[74:75], v[90:91], v[46:47], v[74:75]
	v_pk_fma_f32 v[40:41], v[40:41], v[54:55], v[86:87]
	v_pk_fma_f32 v[86:87], v[52:53], v[122:123], v[136:137]
	v_pk_mul_f32 v[52:53], v[20:21], v[166:167] op_sel_hi:[0,1]
	v_pk_mul_f32 v[52:53], v[52:53], v[128:129]
	s_waitcnt vmcnt(0)
	v_mov_b32_e32 v64, v232
	v_mov_b32_e32 v65, v233
	v_and_b32_e32 v91, 0xffff0000, v65
	v_and_b32_e32 v90, 0xffff0000, v64
	v_lshlrev_b32_e32 v94, 16, v64
	v_lshlrev_b32_e32 v95, 16, v65
	v_pk_fma_f32 v[78:79], v[52:53], v[76:77], v[142:143]
	v_pk_mul_f32 v[52:53], v[20:21], v[162:163] op_sel_hi:[0,1]
	v_pk_mul_f32 v[52:53], v[52:53], v[126:127]
	v_mov_b32_e32 v143, v95
	v_pk_fma_f32 v[52:53], v[52:53], v[8:9], v[24:25]
	v_pk_mul_f32 v[24:25], v[20:21], v[160:161] op_sel_hi:[0,1]
	v_pk_mul_f32 v[24:25], v[24:25], v[4:5]
	v_pk_mul_f32 v[20:21], v[20:21], v[158:159] op_sel_hi:[0,1]
	v_pk_fma_f32 v[24:25], v[24:25], v[132:133], v[70:71]
	v_mov_b32_e32 v71, v94
	v_pk_mul_f32 v[20:21], v[20:21], v[58:59]
	s_waitcnt vmcnt(0)
	v_mov_b32_e32 v64, v234
	v_mov_b32_e32 v65, v235
	v_and_b32_e32 v136, 0xffff0000, v64
	v_and_b32_e32 v137, 0xffff0000, v65
	v_lshlrev_b32_e32 v138, 16, v64
	v_lshlrev_b32_e32 v139, 16, v65
	v_mov_b32_e32 v64, v136
	v_mov_b32_e32 v65, v90
	v_pk_mul_f32 v[64:65], v[64:65], v[64:65]
	v_mov_b32_e32 v70, v138
	v_pk_fma_f32 v[64:65], v[70:71], v[70:71], v[64:65]
	v_mov_b32_e32 v142, v139
	v_pk_fma_f32 v[20:21], v[20:21], v[62:63], v[66:67]
	v_mov_b32_e32 v66, v137
	v_mov_b32_e32 v67, v91
	v_pk_fma_f32 v[64:65], v[142:143], v[142:143], v[64:65]
	s_waitcnt vmcnt(0)
	v_mov_b32_e32 v70, v236
	v_mov_b32_e32 v71, v237
	v_lshlrev_b32_e32 v142, 16, v70
	v_pk_fma_f32 v[66:67], v[66:67], v[66:67], v[64:65]
	v_and_b32_e32 v64, 0xffff0000, v70
	s_waitcnt vmcnt(0)
	v_mov_b32_e32 v134, v238
	v_mov_b32_e32 v135, v239
	v_and_b32_e32 v70, 0xffff0000, v134
	v_and_b32_e32 v65, 0xffff0000, v71
	v_lshlrev_b32_e32 v143, 16, v71
	v_and_b32_e32 v71, 0xffff0000, v135
	v_lshlrev_b32_e32 v144, 16, v134
	v_lshlrev_b32_e32 v145, 16, v135
	v_mov_b32_e32 v134, v70
	v_mov_b32_e32 v135, v64
	v_pk_mul_f32 v[134:135], v[134:135], v[134:135]
	v_mov_b32_e32 v148, v144
	v_mov_b32_e32 v149, v142
	v_mov_b32_e32 v150, v145
	v_mov_b32_e32 v151, v143
	v_pk_fma_f32 v[134:135], v[148:149], v[148:149], v[134:135]
	v_mov_b32_e32 v146, v71
	v_mov_b32_e32 v147, v65
	v_pk_fma_f32 v[134:135], v[150:151], v[150:151], v[134:135]
	s_nop 0
	v_pk_fma_f32 v[154:155], v[146:147], v[146:147], v[134:135]
	v_mov_b32_e32 v134, v16
	v_mov_b32_e32 v135, v18
	v_mov_b32_e32 v18, v17
	s_waitcnt vmcnt(0)
	v_mov_b32_e32 v16, v240
	v_mov_b32_e32 v17, v241
	v_and_b32_e32 v147, 0xffff0000, v17
	v_and_b32_e32 v146, 0xffff0000, v16
	v_lshlrev_b32_e32 v148, 16, v16
	v_lshlrev_b32_e32 v149, 16, v17
	v_mov_b32_e32 v159, v148
	v_mov_b32_e32 v161, v149
	v_mov_b32_e32 v157, v147
	s_waitcnt vmcnt(0)
	v_mov_b32_e32 v16, v242
	v_mov_b32_e32 v17, v243
	v_and_b32_e32 v150, 0xffff0000, v16
	v_and_b32_e32 v151, 0xffff0000, v17
	v_lshlrev_b32_e32 v152, 16, v16
	v_lshlrev_b32_e32 v153, 16, v17
	v_mov_b32_e32 v16, v150
	v_mov_b32_e32 v17, v146
	v_pk_mul_f32 v[16:17], v[16:17], v[16:17]
	v_mov_b32_e32 v158, v152
	v_pk_fma_f32 v[16:17], v[158:159], v[158:159], v[16:17]
	v_mov_b32_e32 v160, v153
	v_mov_b32_e32 v156, v151
	v_pk_fma_f32 v[16:17], v[160:161], v[160:161], v[16:17]
	s_waitcnt vmcnt(0)
	v_mov_b32_e32 v158, v248
	v_mov_b32_e32 v159, v249
	v_mov_b32_e32 v124, v250
	v_mov_b32_e32 v125, v251
	v_and_b32_e32 v160, 0xffff0000, v124
	v_pk_fma_f32 v[16:17], v[156:157], v[156:157], v[16:17]
	v_and_b32_e32 v156, 0xffff0000, v158
	v_lshlrev_b32_e32 v158, 16, v158
	v_lshlrev_b32_e32 v124, 16, v124
	v_mov_b32_e32 v162, v160
	v_mov_b32_e32 v163, v156
	v_and_b32_e32 v157, 0xffff0000, v159
	v_lshlrev_b32_e32 v159, 16, v159
	v_and_b32_e32 v161, 0xffff0000, v125
	v_lshlrev_b32_e32 v125, 16, v125
	v_pk_mul_f32 v[162:163], v[162:163], v[162:163]
	v_mov_b32_e32 v166, v124
	v_mov_b32_e32 v167, v158
	v_mov_b32_e32 v174, v125
	v_mov_b32_e32 v175, v159
	v_pk_fma_f32 v[162:163], v[166:167], v[166:167], v[162:163]
	v_mov_b32_e32 v164, v161
	v_mov_b32_e32 v165, v157
	v_pk_fma_f32 v[162:163], v[174:175], v[174:175], v[162:163]
	s_nop 0
	v_pk_fma_f32 v[162:163], v[164:165], v[164:165], v[162:163]
	v_mov_b32_e32 v165, v154
	v_mov_b32_e32 v164, v162
	v_mov_b32_e32 v154, v163
	v_pk_add_f32 v[154:155], v[164:165], v[154:155]
	v_mov_b32_e32 v162, v16
	v_mov_b32_e32 v163, v66
	v_pk_add_f32 v[154:155], v[154:155], v[162:163]
	v_mov_b32_e32 v66, v17
	v_pk_add_f32 v[16:17], v[154:155], v[66:67]
	s_nop 0
	s_nop 1
	v_add_f32_dpp v17, v17, v17 quad_perm:[1,0,3,2] row_mask:0xf bank_mask:0xf
	v_add_f32_dpp v16, v16, v16 quad_perm:[1,0,3,2] row_mask:0xf bank_mask:0xf
	s_nop 0
	v_add_f32_dpp v17, v17, v17 quad_perm:[2,3,0,1] row_mask:0xf bank_mask:0xf
	v_add_f32_dpp v16, v16, v16 quad_perm:[2,3,0,1] row_mask:0xf bank_mask:0xf
	s_nop 0
	v_add_f32_dpp v17, v17, v17 row_half_mirror row_mask:0xf bank_mask:0xf
	v_add_f32_dpp v16, v16, v16 row_half_mirror row_mask:0xf bank_mask:0xf
	s_nop 0
	v_add_f32_dpp v17, v17, v17 row_mirror row_mask:0xf bank_mask:0xf
	v_add_f32_dpp v16, v16, v16 row_mirror row_mask:0xf bank_mask:0xf
	s_nop 0
	v_mov_b32_e32 v67, v17
	v_mov_b32_e32 v66, v16
	s_nop 0
	v_permlane16_swap_b32_e32 v17, v67
	v_permlane16_swap_b32_e32 v16, v66
	s_nop 0
	v_add_f32_e32 v17, v17, v67
	v_add_f32_e32 v16, v16, v66
	s_nop 0
	v_mov_b32_e32 v67, v17
	v_mov_b32_e32 v66, v16
	s_nop 0
	v_permlane32_swap_b32_e32 v17, v67
	v_permlane32_swap_b32_e32 v16, v66
	s_nop 0
	v_add_f32_e32 v17, v17, v67
	v_add_f32_e32 v16, v16, v66
	s_nop 0
	s_nop 0
	v_pk_fma_f32 v[140:141], v[16:17], s[16:17], v[140:141] op_sel_hi:[1,0,0]
	s_nop 0
	v_mul_f32_e32 v16, 0x4b800000, v141
	v_cmp_gt_f32_e64 s[0:1], s14, v141
	v_cmp_gt_f32_e32 vcc, s14, v140
	s_nop 0
	v_cndmask_b32_e64 v16, v141, v16, s[0:1]
	v_rsq_f32_e32 v16, v16
	s_nop 0
	v_mul_f32_e32 v17, 0x45800000, v16
	v_cndmask_b32_e64 v16, v16, v17, s[0:1]
	v_pk_mul_f32 v[66:67], v[16:17], v[144:145] op_sel_hi:[0,1]
	v_pk_mul_f32 v[70:71], v[16:17], v[70:71] op_sel_hi:[0,1]
	v_pk_mul_f32 v[66:67], v[130:131], v[66:67]
	v_pk_mul_f32 v[144:145], v[34:35], v[70:71]
	v_pk_fma_f32 v[70:71], v[122:123], v[66:67], v[36:37]
	v_pk_fma_f32 v[66:67], v[144:145], v[38:39], v[30:31]
	v_pk_mul_f32 v[30:31], v[16:17], v[142:143] op_sel_hi:[0,1]
	v_pk_mul_f32 v[36:37], v[16:17], v[64:65] op_sel_hi:[0,1]
	v_pk_mul_f32 v[30:31], v[30:31], v[128:129]
	v_pk_mul_f32 v[36:37], v[36:37], v[42:43]
	v_pk_fma_f32 v[64:65], v[30:31], v[76:77], v[72:73]
	v_pk_fma_f32 v[36:37], v[36:37], v[46:47], v[26:27]
	v_pk_mul_f32 v[26:27], v[16:17], v[138:139] op_sel_hi:[0,1]
	v_pk_mul_f32 v[30:31], v[16:17], v[136:137] op_sel_hi:[0,1]
	v_pk_mul_f32 v[26:27], v[26:27], v[126:127]
	v_pk_mul_f32 v[72:73], v[30:31], v[50:51]
	v_pk_fma_f32 v[30:31], v[26:27], v[8:9], v[84:85]
	v_pk_fma_f32 v[26:27], v[72:73], v[54:55], v[22:23]
	v_pk_mul_f32 v[22:23], v[16:17], v[94:95] op_sel_hi:[0,1]
	v_pk_mul_f32 v[16:17], v[16:17], v[90:91] op_sel_hi:[0,1]
	v_pk_mul_f32 v[16:17], v[16:17], v[58:59]
	v_pk_mul_f32 v[22:23], v[22:23], v[4:5]
	v_pk_fma_f32 v[16:17], v[16:17], v[62:63], v[18:19]
	v_mul_f32_e32 v18, 0x4b800000, v140
	v_cndmask_b32_e32 v18, v140, v18, vcc
	v_rsq_f32_e32 v18, v18
	v_pk_fma_f32 v[22:23], v[22:23], v[132:133], v[134:135]
	v_mul_f32_e32 v19, 0x45800000, v18
	v_cndmask_b32_e32 v18, v18, v19, vcc
	v_pk_mul_f32 v[72:73], v[18:19], v[124:125] op_sel_hi:[0,1]
	v_pk_mul_f32 v[84:85], v[18:19], v[160:161] op_sel_hi:[0,1]
	v_pk_mul_f32 v[72:73], v[130:131], v[72:73]
	v_pk_mul_f32 v[34:35], v[34:35], v[84:85]
	v_pk_fma_f32 v[84:85], v[122:123], v[72:73], v[28:29]
	v_pk_fma_f32 v[72:73], v[38:39], v[34:35], v[14:15]
	v_pk_mul_f32 v[14:15], v[18:19], v[158:159] op_sel_hi:[0,1]
	v_pk_mul_f32 v[28:29], v[18:19], v[156:157] op_sel_hi:[0,1]
	v_pk_mul_f32 v[14:15], v[128:129], v[14:15]
	v_pk_mul_f32 v[28:29], v[42:43], v[28:29]
	v_pk_fma_f32 v[42:43], v[14:15], v[76:77], v[44:45]
	v_pk_fma_f32 v[38:39], v[28:29], v[46:47], v[10:11]
	v_pk_mul_f32 v[10:11], v[18:19], v[152:153] op_sel_hi:[0,1]
	v_pk_mul_f32 v[14:15], v[18:19], v[150:151] op_sel_hi:[0,1]
	v_pk_mul_f32 v[10:11], v[10:11], v[126:127]
	v_pk_mul_f32 v[14:15], v[14:15], v[50:51]
	v_pk_fma_f32 v[34:35], v[10:11], v[8:9], v[68:69]
	v_pk_fma_f32 v[28:29], v[14:15], v[54:55], v[6:7]
	v_pk_mul_f32 v[6:7], v[18:19], v[148:149] op_sel_hi:[0,1]
	v_mov_b32_e32 v8, v0
	v_mov_b32_e32 v9, v2
	v_mov_b32_e32 v2, v1
	v_lshlrev_b64 v[0:1], 12, v[104:105]
	v_pk_mul_f32 v[4:5], v[6:7], v[4:5]
	v_pk_mul_f32 v[6:7], v[18:19], v[146:147] op_sel_hi:[0,1]
	v_lshl_add_u64 v[0:1], s[88:89], 0, v[0:1]
	v_pk_mul_f32 v[6:7], v[6:7], v[58:59]
	v_cndmask_b32_e64 v1, v121, v1, s[2:3]
	v_cndmask_b32_e64 v0, v120, v0, s[2:3]
	v_pk_fma_f32 v[14:15], v[4:5], v[132:133], v[8:9]
	v_pk_fma_f32 v[18:19], v[6:7], v[62:63], v[2:3]
	v_lshl_add_u64 v[4:5], v[0:1], 0, v[192:193]
	v_mov_b32_e32 v0, v92
	v_mov_b32_e32 v1, v88
	v_mov_b32_e32 v2, v93
	v_mov_b32_e32 v3, v89
	global_store_dwordx4 v[4:5], v[0:3], off nt
	v_add_co_u32_e32 v6, vcc, s12, v4
	s_nop 0
	v_mov_b32_e32 v0, v80
	v_mov_b32_e32 v1, v60
	v_mov_b32_e32 v2, v81
	v_mov_b32_e32 v3, v61
	global_store_dwordx4 v[4:5], v[0:3], off offset:1024 nt
	v_addc_co_u32_e32 v7, vcc, 0, v5, vcc
	s_nop 0
	v_mov_b32_e32 v0, v56
	v_mov_b32_e32 v1, v40
	v_mov_b32_e32 v2, v57
	v_mov_b32_e32 v3, v41
	global_store_dwordx4 v[4:5], v[0:3], off offset:2048 nt
	v_add_co_u32_e32 v8, vcc, s13, v4
	s_nop 0
	v_mov_b32_e32 v0, v32
	v_mov_b32_e32 v1, v12
	v_mov_b32_e32 v2, v33
	v_mov_b32_e32 v3, v13
	global_store_dwordx4 v[4:5], v[0:3], off offset:3072 nt
	v_addc_co_u32_e32 v9, vcc, 0, v5, vcc
	s_nop 0
	v_mov_b32_e32 v0, v86
	v_mov_b32_e32 v1, v82
	v_mov_b32_e32 v2, v87
	v_mov_b32_e32 v3, v83
	global_store_dwordx4 v[8:9], v[0:3], off offset:-4096 nt
	v_add_co_u32_e32 v4, vcc, s73, v4
	s_nop 0
	v_mov_b32_e32 v0, v78
	v_mov_b32_e32 v1, v74
	v_mov_b32_e32 v2, v79
	v_mov_b32_e32 v3, v75
	global_store_dwordx4 v[6:7], v[0:3], off offset:1024 nt
	v_addc_co_u32_e32 v5, vcc, 0, v5, vcc
	s_nop 0
	v_mov_b32_e32 v0, v52
	v_mov_b32_e32 v1, v48
	v_mov_b32_e32 v2, v53
	v_mov_b32_e32 v3, v49
	global_store_dwordx4 v[6:7], v[0:3], off offset:2048 nt
	s_andn2_b64 vcc, exec, s[4:5]
	s_nop 0
	v_mov_b32_e32 v0, v24
	v_mov_b32_e32 v1, v20
	v_mov_b32_e32 v2, v25
	v_mov_b32_e32 v3, v21
	global_store_dwordx4 v[6:7], v[0:3], off offset:3072 nt
	s_nop 1
	v_mov_b32_e32 v0, v70
	v_mov_b32_e32 v1, v66
	v_mov_b32_e32 v2, v71
	v_mov_b32_e32 v3, v67
	global_store_dwordx4 v[8:9], v[0:3], off nt
	s_nop 1
	v_mov_b32_e32 v0, v64
	v_mov_b32_e32 v1, v36
	v_mov_b32_e32 v2, v65
	v_mov_b32_e32 v3, v37
	global_store_dwordx4 v[8:9], v[0:3], off offset:1024 nt
	s_nop 1
	v_mov_b32_e32 v0, v30
	v_mov_b32_e32 v1, v26
	v_mov_b32_e32 v2, v31
	v_mov_b32_e32 v3, v27
	global_store_dwordx4 v[8:9], v[0:3], off offset:2048 nt
	s_nop 1
	v_mov_b32_e32 v0, v22
	v_mov_b32_e32 v1, v16
	v_mov_b32_e32 v2, v23
	v_mov_b32_e32 v3, v17
	global_store_dwordx4 v[8:9], v[0:3], off offset:3072 nt
	s_nop 1
	v_mov_b32_e32 v0, v84
	v_mov_b32_e32 v1, v72
	v_mov_b32_e32 v2, v85
	v_mov_b32_e32 v3, v73
	global_store_dwordx4 v[4:5], v[0:3], off nt
	s_nop 1
	v_mov_b32_e32 v0, v42
	v_mov_b32_e32 v1, v38
	v_mov_b32_e32 v2, v43
	v_mov_b32_e32 v3, v39
	global_store_dwordx4 v[4:5], v[0:3], off offset:1024 nt
	s_nop 1
	v_mov_b32_e32 v0, v34
	v_mov_b32_e32 v1, v28
	v_mov_b32_e32 v2, v35
	v_mov_b32_e32 v3, v29
	global_store_dwordx4 v[4:5], v[0:3], off offset:2048 nt
	s_nop 1
	v_mov_b32_e32 v0, v14
	v_mov_b32_e32 v1, v18
	v_mov_b32_e32 v2, v15
	v_mov_b32_e32 v3, v19
	global_store_dwordx4 v[4:5], v[0:3], off offset:3072 nt
	s_cbranch_vccnz .LBB0_27
	v_mov_b32_e32 v4, v88
	v_mov_b32_e32 v5, v60
	v_mov_b32_e32 v2, v92
	v_mov_b32_e32 v3, v80
	v_pk_mul_f32 v[4:5], v[4:5], v[4:5]
	v_mov_b32_e32 v6, v40
	v_pk_fma_f32 v[2:3], v[2:3], v[2:3], v[4:5]
	v_mov_b32_e32 v4, v93
	v_mov_b32_e32 v5, v81
	v_pk_fma_f32 v[2:3], v[4:5], v[4:5], v[2:3]
	v_mov_b32_e32 v4, v89
	v_mov_b32_e32 v5, v61
	v_mov_b32_e32 v7, v12
	v_pk_fma_f32 v[2:3], v[4:5], v[4:5], v[2:3]
	v_mov_b32_e32 v4, v56
	v_mov_b32_e32 v5, v32
	v_pk_mul_f32 v[6:7], v[6:7], v[6:7]
	v_mov_b32_e32 v8, v82
	v_pk_fma_f32 v[4:5], v[4:5], v[4:5], v[6:7]
	v_mov_b32_e32 v6, v57
	v_mov_b32_e32 v7, v33
	v_pk_fma_f32 v[4:5], v[6:7], v[6:7], v[4:5]
	v_mov_b32_e32 v6, v41
	v_mov_b32_e32 v7, v13
	v_mov_b32_e32 v9, v74
	v_pk_fma_f32 v[4:5], v[6:7], v[6:7], v[4:5]
	v_mov_b32_e32 v6, v86
	v_mov_b32_e32 v7, v78
	v_pk_mul_f32 v[8:9], v[8:9], v[8:9]
	v_mov_b32_e32 v10, v48
	v_pk_fma_f32 v[6:7], v[6:7], v[6:7], v[8:9]
	v_mov_b32_e32 v8, v87
	v_mov_b32_e32 v9, v79
	v_pk_fma_f32 v[6:7], v[8:9], v[8:9], v[6:7]
	v_mov_b32_e32 v8, v83
	v_mov_b32_e32 v9, v75
	v_mov_b32_e32 v11, v20
	v_pk_fma_f32 v[6:7], v[8:9], v[8:9], v[6:7]
	v_mov_b32_e32 v8, v52
	v_mov_b32_e32 v9, v24
	v_pk_mul_f32 v[10:11], v[10:11], v[10:11]
	s_mov_b32 s0, 0x358637bd
	v_pk_fma_f32 v[8:9], v[8:9], v[8:9], v[10:11]
	v_mov_b32_e32 v10, v53
	v_mov_b32_e32 v11, v25
	v_pk_fma_f32 v[8:9], v[10:11], v[10:11], v[8:9]
	v_mov_b32_e32 v10, v49
	v_mov_b32_e32 v11, v21
	v_pk_fma_f32 v[8:9], v[10:11], v[10:11], v[8:9]
	v_mov_b32_e32 v10, v6
	v_mov_b32_e32 v11, v2
	v_mov_b32_e32 v2, v7
	v_pk_add_f32 v[2:3], v[10:11], v[2:3]
	v_mov_b32_e32 v6, v8
	v_mov_b32_e32 v7, v4
	v_pk_add_f32 v[2:3], v[2:3], v[6:7]
	v_mov_b32_e32 v4, v9
	v_pk_add_f32 v[2:3], v[2:3], v[4:5]
	s_mov_b32 s14, 0x3a800000
	s_mov_b32 s12, 0x800000
	v_mov_b32_e32 v7, v36
	v_mov_b32_e32 v8, v26
	v_mov_b32_e32 v9, v16
	v_pk_mul_f32 v[8:9], v[8:9], v[8:9]
	v_mov_b32_e32 v10, v72
	v_mov_b32_e32 v11, v38
	v_pk_mul_f32 v[10:11], v[10:11], v[10:11]
	v_mov_b32_e32 v50, v28
	v_mov_b32_e32 v51, v18
	v_pk_mul_f32 v[50:51], v[50:51], v[50:51]
	v_add_u32_e32 v0, v172, v168
	v_mul_hi_i32_i24_e32 v1, 0x6000, v0
	v_mul_i32_i24_e32 v0, 0x6000, v0
	v_lshl_add_u64 v[0:1], s[96:97], 0, v[0:1]
	v_lshl_add_u64 v[62:63], v[0:1], 0, v[192:193]
	v_lshl_add_u64 v[58:59], v[102:103], 0, v[118:119]
	s_nop 0
	s_nop 1
	v_add_f32_dpp v3, v3, v3 quad_perm:[1,0,3,2] row_mask:0xf bank_mask:0xf
	v_add_f32_dpp v2, v2, v2 quad_perm:[1,0,3,2] row_mask:0xf bank_mask:0xf
	s_nop 0
	v_add_f32_dpp v3, v3, v3 quad_perm:[2,3,0,1] row_mask:0xf bank_mask:0xf
	v_add_f32_dpp v2, v2, v2 quad_perm:[2,3,0,1] row_mask:0xf bank_mask:0xf
	s_nop 0
	v_add_f32_dpp v3, v3, v3 row_half_mirror row_mask:0xf bank_mask:0xf
	v_add_f32_dpp v2, v2, v2 row_half_mirror row_mask:0xf bank_mask:0xf
	s_nop 0
	v_add_f32_dpp v3, v3, v3 row_mirror row_mask:0xf bank_mask:0xf
	v_add_f32_dpp v2, v2, v2 row_mirror row_mask:0xf bank_mask:0xf
	s_nop 0
	v_mov_b32_e32 v5, v3
	v_mov_b32_e32 v4, v2
	s_nop 0
	v_permlane16_swap_b32_e32 v3, v5
	v_permlane16_swap_b32_e32 v2, v4
	s_nop 0
	v_add_f32_e32 v3, v3, v5
	v_add_f32_e32 v2, v2, v4
	s_nop 0
	v_mov_b32_e32 v5, v3
	v_mov_b32_e32 v4, v2
	s_nop 0
	v_permlane32_swap_b32_e32 v3, v5
	v_permlane32_swap_b32_e32 v2, v4
	s_nop 0
	v_add_f32_e32 v3, v3, v5
	v_add_f32_e32 v2, v2, v4
	s_nop 0
	v_mov_b64_e32 v[4:5], s[0:1]
	v_pk_fma_f32 v[2:3], v[2:3], s[14:15], v[4:5] op_sel_hi:[1,0,0]
	s_nop 0
	v_mul_f32_e32 v6, 0x4b800000, v3
	v_cmp_gt_f32_e64 s[0:1], s12, v3
	v_cmp_gt_f32_e32 vcc, s12, v2
	s_nop 0
	v_cndmask_b32_e64 v3, v3, v6, s[0:1]
	v_rsq_f32_e32 v3, v3
	s_nop 0
	v_mul_f32_e32 v6, 0x45800000, v3
	v_cndmask_b32_e64 v46, v3, v6, s[0:1]
	v_mul_f32_e32 v3, 0x4b800000, v2
	v_cndmask_b32_e32 v2, v2, v3, vcc
	v_rsq_f32_e32 v2, v2
	v_mov_b32_e32 v6, v66
	v_pk_mul_f32 v[6:7], v[6:7], v[6:7]
	v_pk_mul_f32 v[88:89], v[88:89], v[46:47] op_sel_hi:[1,0]
	v_mul_f32_e32 v3, 0x45800000, v2
	v_cndmask_b32_e32 v44, v2, v3, vcc
	v_mov_b32_e32 v2, v70
	v_mov_b32_e32 v3, v64
	v_pk_fma_f32 v[2:3], v[2:3], v[2:3], v[6:7]
	v_mov_b32_e32 v6, v71
	v_mov_b32_e32 v7, v65
	v_pk_fma_f32 v[2:3], v[6:7], v[6:7], v[2:3]
	v_mov_b32_e32 v6, v67
	v_mov_b32_e32 v7, v37
	v_pk_fma_f32 v[2:3], v[6:7], v[6:7], v[2:3]
	v_mov_b32_e32 v6, v30
	v_mov_b32_e32 v7, v22
	v_pk_fma_f32 v[6:7], v[6:7], v[6:7], v[8:9]
	v_mov_b32_e32 v8, v31
	v_mov_b32_e32 v9, v23
	v_pk_fma_f32 v[6:7], v[8:9], v[8:9], v[6:7]
	v_mov_b32_e32 v8, v27
	v_mov_b32_e32 v9, v17
	v_pk_fma_f32 v[6:7], v[8:9], v[8:9], v[6:7]
	v_mov_b32_e32 v8, v84
	v_mov_b32_e32 v9, v42
	v_pk_fma_f32 v[8:9], v[8:9], v[8:9], v[10:11]
	v_mov_b32_e32 v10, v85
	v_mov_b32_e32 v11, v43
	v_pk_fma_f32 v[8:9], v[10:11], v[10:11], v[8:9]
	v_mov_b32_e32 v10, v73
	v_mov_b32_e32 v11, v39
	v_pk_fma_f32 v[8:9], v[10:11], v[10:11], v[8:9]
	v_mov_b32_e32 v10, v34
	v_mov_b32_e32 v11, v14
	v_pk_fma_f32 v[10:11], v[10:11], v[10:11], v[50:51]
	v_mov_b32_e32 v50, v35
	v_mov_b32_e32 v51, v15
	v_pk_fma_f32 v[10:11], v[50:51], v[50:51], v[10:11]
	v_mov_b32_e32 v50, v29
	v_mov_b32_e32 v51, v19
	v_pk_fma_f32 v[10:11], v[50:51], v[50:51], v[10:11]
	v_mov_b32_e32 v50, v8
	v_mov_b32_e32 v51, v2
	v_mov_b32_e32 v2, v9
	v_pk_add_f32 v[2:3], v[50:51], v[2:3]
	v_mov_b32_e32 v8, v10
	v_mov_b32_e32 v9, v6
	v_pk_add_f32 v[2:3], v[2:3], v[8:9]
	v_mov_b32_e32 v6, v11
	v_pk_add_f32 v[2:3], v[2:3], v[6:7]
	v_mov_b32_e32 v107, v193
	v_mov_b32_e32 v109, v193
	v_mov_b32_e32 v111, v193
	s_nop 0
	s_nop 1
	v_add_f32_dpp v3, v3, v3 quad_perm:[1,0,3,2] row_mask:0xf bank_mask:0xf
	v_add_f32_dpp v2, v2, v2 quad_perm:[1,0,3,2] row_mask:0xf bank_mask:0xf
	s_nop 0
	v_add_f32_dpp v3, v3, v3 quad_perm:[2,3,0,1] row_mask:0xf bank_mask:0xf
	v_add_f32_dpp v2, v2, v2 quad_perm:[2,3,0,1] row_mask:0xf bank_mask:0xf
	s_nop 0
	v_add_f32_dpp v3, v3, v3 row_half_mirror row_mask:0xf bank_mask:0xf
	v_add_f32_dpp v2, v2, v2 row_half_mirror row_mask:0xf bank_mask:0xf
	s_nop 0
	v_add_f32_dpp v3, v3, v3 row_mirror row_mask:0xf bank_mask:0xf
	v_add_f32_dpp v2, v2, v2 row_mirror row_mask:0xf bank_mask:0xf
	s_nop 0
	v_mov_b32_e32 v7, v3
	v_mov_b32_e32 v6, v2
	s_nop 0
	v_permlane16_swap_b32_e32 v3, v7
	v_permlane16_swap_b32_e32 v2, v6
	s_nop 0
	v_add_f32_e32 v3, v3, v7
	v_add_f32_e32 v2, v2, v6
	s_nop 0
	v_mov_b32_e32 v7, v3
	v_mov_b32_e32 v6, v2
	s_nop 0
	v_permlane32_swap_b32_e32 v3, v7
	v_permlane32_swap_b32_e32 v2, v6
	s_nop 0
	v_add_f32_e32 v3, v3, v7
	v_add_f32_e32 v2, v2, v6
	s_nop 0
	s_nop 0
	v_pk_fma_f32 v[2:3], v[2:3], s[14:15], v[4:5] op_sel_hi:[1,0,0]
	s_nop 0
	v_mul_f32_e32 v4, 0x4b800000, v3
	v_cmp_gt_f32_e64 s[0:1], s12, v3
	v_cmp_gt_f32_e32 vcc, s12, v2
	s_nop 0
	v_cndmask_b32_e64 v3, v3, v4, s[0:1]
	v_rsq_f32_e32 v3, v3
	s_nop 0
	v_mul_f32_e32 v4, 0x45800000, v3
	v_cndmask_b32_e64 v54, v3, v4, s[0:1]
	v_mul_f32_e32 v3, 0x4b800000, v2
	v_cndmask_b32_e32 v2, v2, v3, vcc
	v_rsq_f32_e32 v2, v2
	s_mov_b64 s[0:1], 0x1000
	v_lshl_add_u64 v[68:69], v[0:1], 0, s[0:1]
	v_lshl_add_u64 v[4:5], v[68:69], 0, v[192:193]
	v_mul_f32_e32 v3, 0x45800000, v2
	v_cndmask_b32_e32 v50, v2, v3, vcc
	global_load_dwordx4 v[0:3], v[100:101], off
	global_load_dwordx4 v[8:11], v[4:5], off
	s_nop 0
	global_load_dwordx4 v[4:7], v[62:63], off
	v_pk_mul_f32 v[66:67], v[66:67], v[54:55] op_sel_hi:[1,0]
	v_pk_mul_f32 v[36:37], v[36:37], v[54:55] op_sel_hi:[1,0]
	v_pk_mul_f32 v[26:27], v[26:27], v[54:55] op_sel_hi:[1,0]
	s_waitcnt vmcnt(2)
	v_mov_b32_e32 v90, v0
	s_waitcnt vmcnt(1)
	v_mov_b32_e32 v76, v8
	v_mov_b32_e32 v77, v10
	v_mov_b32_e32 v10, v9
	v_pk_mul_f32 v[8:9], v[92:93], v[46:47] op_sel_hi:[1,0]
	v_mov_b32_e32 v91, v2
	v_pk_add_f32 v[76:77], v[76:77], 1.0 op_sel_hi:[1,0]
	v_pk_mul_f32 v[8:9], v[8:9], v[90:91]
	s_waitcnt vmcnt(0)
	v_mov_b32_e32 v92, v4
	v_mov_b32_e32 v93, v6
	v_mov_b32_e32 v2, v1
	v_pk_add_f32 v[10:11], v[10:11], 1.0 op_sel_hi:[1,0]
	v_pk_fma_f32 v[8:9], v[8:9], v[76:77], v[92:93]
	v_pk_mul_f32 v[0:1], v[88:89], v[2:3]
	v_mov_b32_e32 v6, v5
	v_pk_fma_f32 v[0:1], v[0:1], v[10:11], v[6:7]
	v_cvt_pk_bf16_f32 v0, v8, v0
	v_cvt_pk_bf16_f32 v1, v9, v1
	v_pk_mul_f32 v[4:5], v[86:87], v[44:45] op_sel_hi:[1,0]
	v_pk_mul_f32 v[8:9], v[82:83], v[44:45] op_sel_hi:[1,0]
	v_pk_mul_f32 v[4:5], v[4:5], v[90:91]
	v_pk_mul_f32 v[8:9], v[8:9], v[2:3]
	v_pk_fma_f32 v[4:5], v[4:5], v[76:77], v[92:93]
	v_pk_fma_f32 v[8:9], v[8:9], v[10:11], v[6:7]
	v_cvt_pk_bf16_f32 v5, v5, v9
	v_cvt_pk_bf16_f32 v4, v4, v8
	v_pk_mul_f32 v[8:9], v[70:71], v[54:55] op_sel_hi:[1,0]
	v_pk_mul_f32 v[66:67], v[2:3], v[66:67]
	v_pk_mul_f32 v[8:9], v[90:91], v[8:9]
	v_pk_fma_f32 v[66:67], v[66:67], v[10:11], v[6:7]
	v_pk_fma_f32 v[8:9], v[8:9], v[76:77], v[92:93]
	v_pk_mul_f32 v[70:71], v[72:73], v[50:51] op_sel_hi:[1,0]
	v_cvt_pk_bf16_f32 v9, v9, v67
	v_and_b32_sdwa v47, v8, v218 dst_sel:DWORD dst_unused:UNUSED_PAD src0_sel:WORD_1 src1_sel:DWORD
	v_add3_u32 v8, v8, v47, s80
	v_and_b32_sdwa v47, v66, v218 dst_sel:DWORD dst_unused:UNUSED_PAD src0_sel:WORD_1 src1_sel:DWORD
	v_add3_u32 v47, v66, v47, s80
	v_pk_mul_f32 v[66:67], v[84:85], v[50:51] op_sel_hi:[1,0]
	v_pk_mul_f32 v[2:3], v[2:3], v[70:71]
	v_pk_mul_f32 v[66:67], v[90:91], v[66:67]
	v_pk_fma_f32 v[2:3], v[10:11], v[2:3], v[6:7]
	v_pk_fma_f32 v[66:67], v[76:77], v[66:67], v[92:93]
	global_store_dwordx2 v[58:59], v[0:1], off nt
	v_lshl_add_u64 v[0:1], v[102:103], 0, v[116:117]
	v_and_b32_e32 v47, 0xffff0000, v47
	v_cvt_pk_bf16_f32 v3, v67, v3
	v_cvt_pk_bf16_f32 v2, v66, v2
	global_store_dwordx2 v[0:1], v[4:5], off nt
	v_lshl_add_u64 v[4:5], v[102:103], 0, v[114:115]
	v_or_b32_sdwa v8, v47, v8 dst_sel:DWORD dst_unused:UNUSED_PAD src0_sel:DWORD src1_sel:WORD_1
	global_store_dwordx2 v[4:5], v[8:9], off nt
	v_lshl_add_u64 v[8:9], v[102:103], 0, v[112:113]
	global_store_dwordx2 v[8:9], v[2:3], off nt
	v_lshl_add_u64 v[2:3], v[68:69], 0, v[106:107]
	global_load_dwordx4 v[70:73], v[100:101], off offset:1024
	global_load_dwordx4 v[82:85], v[2:3], off
	global_load_dwordx4 v[86:89], v[62:63], off offset:1024
	v_pk_mul_f32 v[10:11], v[80:81], v[46:47] op_sel_hi:[1,0]
	v_pk_mul_f32 v[60:61], v[60:61], v[46:47] op_sel_hi:[1,0]
	s_waitcnt vmcnt(2)
	v_mov_b32_e32 v66, v70
	s_waitcnt vmcnt(1)
	v_mov_b32_e32 v2, v82
	v_mov_b32_e32 v3, v84
	v_mov_b32_e32 v67, v72
	v_pk_add_f32 v[2:3], v[2:3], 1.0 op_sel_hi:[1,0]
	v_mov_b32_e32 v84, v83
	v_pk_mul_f32 v[10:11], v[10:11], v[66:67]
	s_waitcnt vmcnt(0)
	v_mov_b32_e32 v76, v86
	v_mov_b32_e32 v77, v88
	v_mov_b32_e32 v72, v71
	v_pk_add_f32 v[6:7], v[84:85], 1.0 op_sel_hi:[1,0]
	v_pk_fma_f32 v[10:11], v[10:11], v[2:3], v[76:77]
	v_pk_mul_f32 v[60:61], v[60:61], v[72:73]
	v_mov_b32_e32 v88, v87
	v_pk_fma_f32 v[60:61], v[60:61], v[6:7], v[88:89]
	v_and_b32_sdwa v45, v11, v218 dst_sel:DWORD dst_unused:UNUSED_PAD src0_sel:WORD_1 src1_sel:DWORD
	v_cvt_pk_bf16_f32 v10, v10, v60
	v_add3_u32 v11, v11, v45, s80
	v_and_b32_sdwa v45, v61, v218 dst_sel:DWORD dst_unused:UNUSED_PAD src0_sel:WORD_1 src1_sel:DWORD
	v_add3_u32 v45, v61, v45, s80
	v_and_b32_e32 v45, 0xffff0000, v45
	v_or_b32_sdwa v11, v45, v11 dst_sel:DWORD dst_unused:UNUSED_PAD src0_sel:DWORD src1_sel:WORD_1
	global_store_dwordx2 v[58:59], v[10:11], off offset:512 nt
	v_pk_mul_f32 v[10:11], v[78:79], v[44:45] op_sel_hi:[1,0]
	v_pk_mul_f32 v[60:61], v[74:75], v[44:45] op_sel_hi:[1,0]
	v_pk_mul_f32 v[10:11], v[10:11], v[66:67]
	v_pk_mul_f32 v[60:61], v[60:61], v[72:73]
	v_pk_fma_f32 v[10:11], v[10:11], v[2:3], v[76:77]
	v_pk_fma_f32 v[60:61], v[60:61], v[6:7], v[88:89]
	v_cvt_pk_bf16_f32 v11, v11, v61
	v_cvt_pk_bf16_f32 v10, v10, v60
	global_store_dwordx2 v[0:1], v[10:11], off offset:512 nt
	v_pk_mul_f32 v[10:11], v[64:65], v[54:55] op_sel_hi:[1,0]
	v_pk_mul_f32 v[36:37], v[36:37], v[72:73]
	v_pk_mul_f32 v[10:11], v[10:11], v[66:67]
	v_pk_fma_f32 v[36:37], v[36:37], v[6:7], v[88:89]
	v_pk_fma_f32 v[10:11], v[10:11], v[2:3], v[76:77]
	s_nop 0
	v_and_b32_sdwa v45, v11, v218 dst_sel:DWORD dst_unused:UNUSED_PAD src0_sel:WORD_1 src1_sel:DWORD
	v_and_b32_sdwa v47, v10, v218 dst_sel:DWORD dst_unused:UNUSED_PAD src0_sel:WORD_1 src1_sel:DWORD
	v_add3_u32 v10, v10, v47, s80
	v_add3_u32 v11, v11, v45, s80
	v_and_b32_sdwa v45, v37, v218 dst_sel:DWORD dst_unused:UNUSED_PAD src0_sel:WORD_1 src1_sel:DWORD
	v_and_b32_sdwa v47, v36, v218 dst_sel:DWORD dst_unused:UNUSED_PAD src0_sel:WORD_1 src1_sel:DWORD
	v_add3_u32 v37, v37, v45, s80
	v_add3_u32 v36, v36, v47, s80
	v_and_b32_e32 v37, 0xffff0000, v37
	v_and_b32_e32 v36, 0xffff0000, v36
	v_or_b32_sdwa v11, v37, v11 dst_sel:DWORD dst_unused:UNUSED_PAD src0_sel:DWORD src1_sel:WORD_1
	v_or_b32_sdwa v10, v36, v10 dst_sel:DWORD dst_unused:UNUSED_PAD src0_sel:DWORD src1_sel:WORD_1
	global_store_dwordx2 v[4:5], v[10:11], off offset:512 nt
	v_pk_mul_f32 v[10:11], v[42:43], v[50:51] op_sel_hi:[1,0]
	v_pk_mul_f32 v[40:41], v[40:41], v[46:47] op_sel_hi:[1,0]
	v_pk_mul_f32 v[10:11], v[10:11], v[66:67]
	v_pk_mul_f32 v[12:13], v[12:13], v[46:47] op_sel_hi:[1,0]
	v_pk_fma_f32 v[2:3], v[10:11], v[2:3], v[76:77]
	v_pk_mul_f32 v[10:11], v[38:39], v[50:51] op_sel_hi:[1,0]
	s_nop 0
	v_pk_mul_f32 v[10:11], v[10:11], v[72:73]
	s_nop 0
	v_pk_fma_f32 v[6:7], v[10:11], v[6:7], v[88:89]
	v_cvt_pk_bf16_f32 v3, v3, v7
	v_cvt_pk_bf16_f32 v2, v2, v6
	global_store_dwordx2 v[8:9], v[2:3], off offset:512 nt
	v_lshl_add_u64 v[2:3], v[68:69], 0, v[108:109]
	global_load_dwordx4 v[36:39], v[100:101], off offset:2048
	global_load_dwordx4 v[64:67], v[2:3], off
	global_load_dwordx4 v[70:73], v[62:63], off offset:2048
	v_pk_mul_f32 v[10:11], v[56:57], v[46:47] op_sel_hi:[1,0]
	s_waitcnt vmcnt(2)
	v_mov_b32_e32 v42, v36
	s_waitcnt vmcnt(1)
	v_mov_b32_e32 v2, v64
	v_mov_b32_e32 v3, v66
	v_mov_b32_e32 v43, v38
	v_pk_add_f32 v[2:3], v[2:3], 1.0 op_sel_hi:[1,0]
	v_mov_b32_e32 v66, v65
	v_pk_mul_f32 v[10:11], v[10:11], v[42:43]
	s_waitcnt vmcnt(0)
	v_mov_b32_e32 v56, v70
	v_mov_b32_e32 v57, v72
	v_mov_b32_e32 v38, v37
	v_pk_add_f32 v[6:7], v[66:67], 1.0 op_sel_hi:[1,0]
	v_pk_fma_f32 v[10:11], v[10:11], v[2:3], v[56:57]
	v_pk_mul_f32 v[36:37], v[40:41], v[38:39]
	v_mov_b32_e32 v72, v71
	v_pk_fma_f32 v[36:37], v[36:37], v[6:7], v[72:73]
	v_cvt_pk_bf16_f32 v11, v11, v37
	v_cvt_pk_bf16_f32 v10, v10, v36
	global_store_dwordx2 v[58:59], v[10:11], off offset:1024 nt
	v_pk_mul_f32 v[10:11], v[52:53], v[44:45] op_sel_hi:[1,0]
	v_pk_mul_f32 v[36:37], v[48:49], v[44:45] op_sel_hi:[1,0]
	v_pk_mul_f32 v[10:11], v[10:11], v[42:43]
	v_pk_mul_f32 v[36:37], v[36:37], v[38:39]
	v_pk_fma_f32 v[10:11], v[10:11], v[2:3], v[56:57]
	v_pk_fma_f32 v[36:37], v[36:37], v[6:7], v[72:73]
	v_cvt_pk_bf16_f32 v11, v11, v37
	v_cvt_pk_bf16_f32 v10, v10, v36
	global_store_dwordx2 v[0:1], v[10:11], off offset:1024 nt
	v_pk_mul_f32 v[10:11], v[30:31], v[54:55] op_sel_hi:[1,0]
	v_pk_mul_f32 v[26:27], v[26:27], v[38:39]
	v_pk_mul_f32 v[10:11], v[10:11], v[42:43]
	v_pk_fma_f32 v[26:27], v[26:27], v[6:7], v[72:73]
	v_pk_fma_f32 v[10:11], v[10:11], v[2:3], v[56:57]
	s_nop 0
	v_cvt_pk_bf16_f32 v11, v11, v27
	v_cvt_pk_bf16_f32 v10, v10, v26
	global_store_dwordx2 v[4:5], v[10:11], off offset:1024 nt
	v_pk_mul_f32 v[10:11], v[34:35], v[50:51] op_sel_hi:[1,0]
	s_nop 0
	v_pk_mul_f32 v[10:11], v[10:11], v[42:43]
	s_nop 0
	v_pk_fma_f32 v[2:3], v[10:11], v[2:3], v[56:57]
	v_pk_mul_f32 v[10:11], v[28:29], v[50:51] op_sel_hi:[1,0]
	s_nop 0
	v_pk_mul_f32 v[10:11], v[10:11], v[38:39]
	s_nop 0
	v_pk_fma_f32 v[6:7], v[10:11], v[6:7], v[72:73]
	v_cvt_pk_bf16_f32 v3, v3, v7
	v_cvt_pk_bf16_f32 v2, v2, v6
	global_store_dwordx2 v[8:9], v[2:3], off offset:1024 nt
	v_lshl_add_u64 v[2:3], v[68:69], 0, v[110:111]
	global_load_dwordx4 v[26:29], v[100:101], off offset:3072
	global_load_dwordx4 v[34:37], v[2:3], off
	global_load_dwordx4 v[38:41], v[62:63], off offset:3072
	v_pk_mul_f32 v[10:11], v[32:33], v[46:47] op_sel_hi:[1,0]
	s_waitcnt vmcnt(2)
	v_mov_b32_e32 v30, v26
	s_waitcnt vmcnt(1)
	v_mov_b32_e32 v2, v34
	v_mov_b32_e32 v3, v36
	v_mov_b32_e32 v31, v28
	v_pk_add_f32 v[2:3], v[2:3], 1.0 op_sel_hi:[1,0]
	v_mov_b32_e32 v36, v35
	v_pk_mul_f32 v[10:11], v[10:11], v[30:31]
	s_waitcnt vmcnt(0)
	v_mov_b32_e32 v32, v38
	v_mov_b32_e32 v33, v40
	v_mov_b32_e32 v28, v27
	v_pk_add_f32 v[6:7], v[36:37], 1.0 op_sel_hi:[1,0]
	v_pk_fma_f32 v[10:11], v[10:11], v[2:3], v[32:33]
	v_pk_mul_f32 v[12:13], v[12:13], v[28:29]
	v_mov_b32_e32 v40, v39
	v_pk_fma_f32 v[12:13], v[12:13], v[6:7], v[40:41]
	v_cvt_pk_bf16_f32 v11, v11, v13
	v_cvt_pk_bf16_f32 v10, v10, v12
	global_store_dwordx2 v[58:59], v[10:11], off offset:1536 nt
	v_pk_mul_f32 v[10:11], v[24:25], v[44:45] op_sel_hi:[1,0]
	v_pk_mul_f32 v[12:13], v[20:21], v[44:45] op_sel_hi:[1,0]
	v_pk_mul_f32 v[10:11], v[10:11], v[30:31]
	v_pk_mul_f32 v[12:13], v[12:13], v[28:29]
	v_pk_fma_f32 v[10:11], v[10:11], v[2:3], v[32:33]
	v_pk_fma_f32 v[12:13], v[12:13], v[6:7], v[40:41]
	v_cvt_pk_bf16_f32 v11, v11, v13
	v_cvt_pk_bf16_f32 v10, v10, v12
	global_store_dwordx2 v[0:1], v[10:11], off offset:1536 nt
	v_pk_mul_f32 v[0:1], v[22:23], v[54:55] op_sel_hi:[1,0]
	v_pk_mul_f32 v[10:11], v[16:17], v[54:55] op_sel_hi:[1,0]
	v_pk_mul_f32 v[0:1], v[0:1], v[30:31]
	v_pk_mul_f32 v[10:11], v[10:11], v[28:29]
	v_pk_fma_f32 v[0:1], v[0:1], v[2:3], v[32:33]
	v_pk_fma_f32 v[10:11], v[10:11], v[6:7], v[40:41]
	v_cvt_pk_bf16_f32 v1, v1, v11
	v_cvt_pk_bf16_f32 v0, v0, v10
	global_store_dwordx2 v[4:5], v[0:1], off offset:1536 nt
	v_pk_mul_f32 v[0:1], v[14:15], v[50:51] op_sel_hi:[1,0]
	s_nop 0
	v_pk_mul_f32 v[0:1], v[0:1], v[30:31]
	s_nop 0
	v_pk_fma_f32 v[0:1], v[0:1], v[2:3], v[32:33]
	v_pk_mul_f32 v[2:3], v[18:19], v[50:51] op_sel_hi:[1,0]
	v_and_b32_sdwa v4, v1, v218 dst_sel:DWORD dst_unused:UNUSED_PAD src0_sel:WORD_1 src1_sel:DWORD
	v_pk_mul_f32 v[2:3], v[2:3], v[28:29]
	v_and_b32_sdwa v5, v0, v218 dst_sel:DWORD dst_unused:UNUSED_PAD src0_sel:WORD_1 src1_sel:DWORD
	v_pk_fma_f32 v[2:3], v[2:3], v[6:7], v[40:41]
	v_add3_u32 v0, v0, v5, s80
	v_add3_u32 v1, v1, v4, s80
	v_and_b32_sdwa v4, v3, v218 dst_sel:DWORD dst_unused:UNUSED_PAD src0_sel:WORD_1 src1_sel:DWORD
	v_and_b32_sdwa v5, v2, v218 dst_sel:DWORD dst_unused:UNUSED_PAD src0_sel:WORD_1 src1_sel:DWORD
	v_add3_u32 v3, v3, v4, s80
	v_add3_u32 v2, v2, v5, s80
	v_and_b32_e32 v3, 0xffff0000, v3
	v_and_b32_e32 v2, 0xffff0000, v2
	v_or_b32_sdwa v1, v3, v1 dst_sel:DWORD dst_unused:UNUSED_PAD src0_sel:DWORD src1_sel:WORD_1
	v_or_b32_sdwa v0, v2, v0 dst_sel:DWORD dst_unused:UNUSED_PAD src0_sel:DWORD src1_sel:WORD_1
	global_store_dwordx2 v[8:9], v[0:1], off offset:1536 nt
	s_branch .LBB0_27

.LBB0_34:
	v_cmp_gt_i32_e32 vcc, 0, v40
	v_min_i32_e32 v0, 0x4000, v26
	v_mov_b32_e32 v2, s23
	v_mov_b32_e32 v3, s89
	v_ashrrev_i32_e32 v31, 13, v0
	v_cndmask_b32_e32 v1, 0, v27, vcc
	v_cndmask_b32_e32 v0, v40, v26, vcc
	v_cndmask_b32_e32 v3, v2, v3, vcc
	v_mov_b32_e32 v2, s22
	v_mov_b32_e32 v4, s88
	v_cndmask_b32_e32 v2, v2, v4, vcc
	v_lshlrev_b64 v[0:1], 12, v[0:1]
	v_lshl_add_u64 v[0:1], v[2:3], 0, v[0:1]
	v_lshl_add_u64 v[36:37], v[0:1], 0, v[192:193]
	global_load_dwordx4 v[12:15], v[36:37], off nt
	global_load_dwordx4 v[8:11], v[36:37], off offset:1024 nt
	global_load_dwordx4 v[4:7], v[36:37], off offset:2048 nt
	global_load_dwordx4 v[0:3], v[36:37], off offset:3072 nt
	global_load_dwordx2 v[56:57], v[28:29], off nt
	global_load_dwordx2 v[64:65], v[28:29], off offset:512 nt
	global_load_dwordx2 v[72:73], v[28:29], off offset:1024 nt
	global_load_dwordx2 v[80:81], v[28:29], off offset:1536 nt
	v_mul_hi_i32_i24_e32 v39, 0x6000, v31
	v_mul_i32_i24_e32 v38, 0x6000, v31
	v_lshl_add_u64 v[38:39], s[90:91], 0, v[38:39]
	s_waitcnt vmcnt(11)
	v_lshl_add_u64 v[52:53], v[38:39], 0, v[192:193]
	v_lshl_add_u64 v[76:77], v[52:53], 0, s[34:35]
	v_add_co_u32_e32 v52, vcc, s24, v52
	global_load_dwordx4 v[48:51], v[16:17], off
	s_nop 0
	v_addc_co_u32_e32 v53, vcc, 0, v53, vcc
	global_load_dwordx4 v[52:55], v[52:53], off
	s_mov_b32 s4, 0xf823c000
	v_add_u32_e32 v40, s20, v40
	v_lshl_add_u64 v[26:27], v[26:27], 0, s[20:21]
	s_waitcnt vmcnt(5)
	v_and_b32_e32 v39, 0xffff0000, v56
	s_waitcnt vmcnt(4)
	v_and_b32_e32 v85, 0xffff0000, v64
	v_lshlrev_b32_e32 v38, 16, v56
	v_lshlrev_b32_e32 v84, 16, v64
	v_mov_b32_e32 v66, v39
	v_mov_b32_e32 v67, v85
	v_lshlrev_b32_e32 v82, 16, v57
	v_and_b32_e32 v87, 0xffff0000, v65
	v_lshlrev_b32_e32 v86, 16, v65
	v_mov_b32_e32 v64, v38
	v_mov_b32_e32 v65, v84
	v_pk_mul_f32 v[66:67], v[66:67], v[66:67]
	v_and_b32_e32 v83, 0xffff0000, v57
	global_load_dwordx4 v[56:59], v[16:17], off offset:1024
	global_load_dwordx4 v[60:63], v[76:77], off offset:1024
	v_pk_fma_f32 v[64:65], v[64:65], v[64:65], v[66:67]
	v_mov_b32_e32 v66, v82
	v_mov_b32_e32 v67, v86
	v_mov_b32_e32 v68, v83
	v_mov_b32_e32 v69, v87
	v_pk_fma_f32 v[64:65], v[66:67], v[66:67], v[64:65]
	s_waitcnt vmcnt(5)
	v_and_b32_e32 v91, 0xffff0000, v72
	v_pk_fma_f32 v[88:89], v[68:69], v[68:69], v[64:65]
	global_load_dwordx4 v[64:67], v[16:17], off offset:2048
	global_load_dwordx4 v[68:71], v[76:77], off offset:2048
	v_lshlrev_b32_e32 v90, 16, v72
	v_and_b32_e32 v93, 0xffff0000, v73
	v_lshlrev_b32_e32 v92, 16, v73
	global_load_dwordx4 v[72:75], v[16:17], off offset:3072
	s_nop 0
	global_load_dwordx4 v[76:79], v[76:77], off offset:3072
	s_waitcnt vmcnt(8)
	v_and_b32_e32 v95, 0xffff0000, v80
	v_lshlrev_b32_e32 v94, 16, v80
	v_mov_b32_e32 v98, v91
	v_mov_b32_e32 v99, v95
	v_and_b32_e32 v97, 0xffff0000, v81
	v_lshlrev_b32_e32 v96, 16, v81
	v_mov_b32_e32 v80, v90
	v_mov_b32_e32 v81, v94
	v_pk_mul_f32 v[98:99], v[98:99], v[98:99]
	v_mov_b32_e32 v100, v93
	v_pk_fma_f32 v[80:81], v[80:81], v[80:81], v[98:99]
	v_mov_b32_e32 v98, v92
	v_mov_b32_e32 v99, v96
	v_mov_b32_e32 v101, v97
	v_pk_fma_f32 v[80:81], v[98:99], v[98:99], v[80:81]
	v_add_f32_e32 v33, v88, v89
	v_pk_fma_f32 v[80:81], v[100:101], v[100:101], v[80:81]
	s_nop 0
	v_add_f32_e32 v33, v33, v80
	v_add_f32_e32 v33, v33, v81
	s_nop 0
	s_nop 1
	v_add_f32_dpp v33, v33, v33 quad_perm:[1,0,3,2] row_mask:0xf bank_mask:0xf
	s_nop 1
	v_add_f32_dpp v33, v33, v33 quad_perm:[2,3,0,1] row_mask:0xf bank_mask:0xf
	s_nop 1
	v_add_f32_dpp v33, v33, v33 row_half_mirror row_mask:0xf bank_mask:0xf
	s_nop 1
	v_add_f32_dpp v33, v33, v33 row_mirror row_mask:0xf bank_mask:0xf
	s_nop 1
	v_mov_b32_e32 v35, v33
	s_nop 1
	v_permlane16_swap_b32_e32 v33, v35
	s_nop 1
	v_add_f32_e32 v33, v33, v35
	s_nop 1
	v_mov_b32_e32 v35, v33
	s_nop 1
	v_permlane32_swap_b32_e32 v33, v35
	s_nop 1
	v_add_f32_e32 v33, v33, v35
	s_nop 1
	v_fmamk_f32 v33, v33, 0x3a800000, v219
	v_cmp_gt_f32_e32 vcc, s25, v33
	v_mul_f32_e32 v35, 0x4b800000, v33
	s_nop 0
	v_cndmask_b32_e32 v33, v33, v35, vcc
	v_rsq_f32_e32 v33, v33
	s_nop 0
	v_mul_f32_e32 v35, 0x45800000, v33
	v_cndmask_b32_e32 v80, v33, v35, vcc
	v_pk_mul_f32 v[38:39], v[80:81], v[38:39] op_sel_hi:[0,1]
	s_waitcnt vmcnt(7)
	v_pk_mul_f32 v[38:39], v[48:49], v[38:39]
	v_pk_mul_f32 v[48:49], v[80:81], v[82:83] op_sel_hi:[0,1]
	v_pk_mul_f32 v[50:51], v[50:51], v[48:49]
	s_waitcnt vmcnt(6)
	v_pk_fma_f32 v[48:49], v[52:53], v[38:39], v[12:13]
	v_pk_mul_f32 v[12:13], v[80:81], v[84:85] op_sel_hi:[0,1]
	v_pk_fma_f32 v[50:51], v[54:55], v[50:51], v[14:15]
	s_waitcnt vmcnt(5)
	v_pk_mul_f32 v[12:13], v[56:57], v[12:13]
	v_pk_mul_f32 v[14:15], v[80:81], v[86:87] op_sel_hi:[0,1]
	v_pk_mul_f32 v[14:15], v[58:59], v[14:15]
	s_waitcnt vmcnt(4)
	v_pk_fma_f32 v[8:9], v[60:61], v[12:13], v[8:9]
	v_pk_mul_f32 v[12:13], v[80:81], v[90:91] op_sel_hi:[0,1]
	v_pk_fma_f32 v[10:11], v[62:63], v[14:15], v[10:11]
	s_waitcnt vmcnt(3)
	v_pk_mul_f32 v[12:13], v[12:13], v[64:65]
	v_pk_mul_f32 v[14:15], v[80:81], v[92:93] op_sel_hi:[0,1]
	v_pk_mul_f32 v[14:15], v[14:15], v[66:67]
	s_waitcnt vmcnt(2)
	v_pk_fma_f32 v[4:5], v[12:13], v[68:69], v[4:5]
	v_pk_mul_f32 v[12:13], v[80:81], v[94:95] op_sel_hi:[0,1]
	v_pk_fma_f32 v[6:7], v[14:15], v[70:71], v[6:7]
	s_waitcnt vmcnt(1)
	v_pk_mul_f32 v[12:13], v[12:13], v[72:73]
	v_pk_mul_f32 v[14:15], v[80:81], v[96:97] op_sel_hi:[0,1]
	v_pk_mul_f32 v[14:15], v[14:15], v[74:75]
	s_waitcnt vmcnt(0)
	v_pk_fma_f32 v[0:1], v[12:13], v[76:77], v[0:1]
	v_add_u32_e32 v12, 3, v31
	v_pk_fma_f32 v[2:3], v[14:15], v[78:79], v[2:3]
	global_store_dwordx4 v[36:37], v[48:51], off nt
	global_store_dwordx4 v[36:37], v[8:11], off offset:1024 nt
	global_store_dwordx4 v[36:37], v[4:7], off offset:2048 nt
	global_store_dwordx4 v[36:37], v[0:3], off offset:3072 nt
	v_mul_hi_i32_i24_e32 v13, 0x6000, v12
	v_mul_i32_i24_e32 v12, 0x6000, v12
	v_mov_b32_e32 v36, v49
	v_mov_b32_e32 v37, v9
	v_lshl_add_u64 v[14:15], s[96:97], 0, v[12:13]
	v_mov_b32_e32 v12, v48
	v_mov_b32_e32 v13, v8
	v_pk_mul_f32 v[36:37], v[36:37], v[36:37]
	v_mov_b32_e32 v38, v5
	v_pk_fma_f32 v[12:13], v[12:13], v[12:13], v[36:37]
	v_mov_b32_e32 v36, v50
	v_mov_b32_e32 v37, v10
	v_pk_fma_f32 v[12:13], v[36:37], v[36:37], v[12:13]
	v_mov_b32_e32 v36, v51
	v_mov_b32_e32 v37, v11
	v_mov_b32_e32 v39, v1
	v_pk_fma_f32 v[12:13], v[36:37], v[36:37], v[12:13]
	v_mov_b32_e32 v36, v4
	v_mov_b32_e32 v37, v0
	v_pk_mul_f32 v[38:39], v[38:39], v[38:39]
	v_add_f32_e32 v12, v12, v13
	v_pk_fma_f32 v[36:37], v[36:37], v[36:37], v[38:39]
	v_mov_b32_e32 v38, v6
	v_mov_b32_e32 v39, v2
	v_pk_fma_f32 v[36:37], v[38:39], v[38:39], v[36:37]
	v_mov_b32_e32 v38, v7
	v_mov_b32_e32 v39, v3
	v_pk_fma_f32 v[36:37], v[38:39], v[38:39], v[36:37]
	s_nop 0
	v_add_f32_e32 v12, v12, v36
	v_add_f32_e32 v12, v12, v37
	v_lshl_add_u64 v[36:37], v[14:15], 0, s[28:29]
	v_lshl_add_u64 v[38:39], v[36:37], 0, v[192:193]
	v_lshl_add_u64 v[14:15], v[14:15], 0, v[192:193]
	global_load_dwordx4 v[52:55], v[18:19], off
	global_load_dwordx4 v[56:59], v[38:39], off
	global_load_dwordx4 v[60:63], v[14:15], off
	v_mov_b32_e32 v38, v48
	v_mov_b32_e32 v39, v50
	v_mov_b32_e32 v50, v49
	s_nop 0
	s_nop 1
	v_add_f32_dpp v12, v12, v12 quad_perm:[1,0,3,2] row_mask:0xf bank_mask:0xf
	s_nop 1
	v_add_f32_dpp v12, v12, v12 quad_perm:[2,3,0,1] row_mask:0xf bank_mask:0xf
	s_nop 1
	v_add_f32_dpp v12, v12, v12 row_half_mirror row_mask:0xf bank_mask:0xf
	s_nop 1
	v_add_f32_dpp v12, v12, v12 row_mirror row_mask:0xf bank_mask:0xf
	s_nop 1
	v_mov_b32_e32 v13, v12
	s_nop 1
	v_permlane16_swap_b32_e32 v12, v13
	s_nop 1
	v_add_f32_e32 v12, v12, v13
	s_nop 1
	v_mov_b32_e32 v13, v12
	s_nop 1
	v_permlane32_swap_b32_e32 v12, v13
	s_nop 1
	v_add_f32_e32 v12, v12, v13
	s_nop 1
	v_fmamk_f32 v12, v12, 0x3a800000, v219
	v_cmp_gt_f32_e32 vcc, s25, v12
	v_mul_f32_e32 v13, 0x4b800000, v12
	s_waitcnt vmcnt(2)
	v_mov_b32_e32 v64, v52
	v_cndmask_b32_e32 v12, v12, v13, vcc
	v_rsq_f32_e32 v12, v12
	v_mov_b32_e32 v65, v54
	v_mov_b32_e32 v54, v53
	s_waitcnt vmcnt(0)
	v_mov_b32_e32 v67, v62
	v_mul_f32_e32 v13, 0x45800000, v12
	v_cndmask_b32_e32 v12, v12, v13, vcc
	v_pk_mul_f32 v[38:39], v[38:39], v[12:13] op_sel_hi:[1,0]
	v_pk_mul_f32 v[48:49], v[50:51], v[12:13] op_sel_hi:[1,0]
	v_pk_mul_f32 v[38:39], v[64:65], v[38:39]
	v_mov_b32_e32 v65, v58
	v_mov_b32_e32 v58, v57
	v_mov_b32_e32 v64, v56
	v_pk_mul_f32 v[48:49], v[54:55], v[48:49]
	v_pk_add_f32 v[50:51], v[58:59], 1.0 op_sel_hi:[1,0]
	v_mov_b32_e32 v62, v61
	v_pk_add_f32 v[64:65], v[64:65], 1.0 op_sel_hi:[1,0]
	v_mov_b32_e32 v66, v60
	v_pk_fma_f32 v[48:49], v[50:51], v[48:49], v[62:63]
	v_pk_fma_f32 v[38:39], v[64:65], v[38:39], v[66:67]
	v_and_b32_sdwa v33, v49, v218 dst_sel:DWORD dst_unused:UNUSED_PAD src0_sel:WORD_1 src1_sel:DWORD
	v_and_b32_sdwa v13, v39, v218 dst_sel:DWORD dst_unused:UNUSED_PAD src0_sel:WORD_1 src1_sel:DWORD
	v_cvt_pk_bf16_f32 v38, v38, v48
	v_add3_u32 v33, v49, v33, s80
	v_add3_u32 v13, v39, v13, s80
	v_and_b32_e32 v33, 0xffff0000, v33
	v_add_co_u32_e32 v48, vcc, s4, v28
	v_or_b32_sdwa v39, v33, v13 dst_sel:DWORD dst_unused:UNUSED_PAD src0_sel:DWORD src1_sel:WORD_1
	s_nop 0
	v_addc_co_u32_e32 v49, vcc, -1, v29, vcc
	global_store_dwordx2 v[48:49], v[38:39], off nt
	v_mov_b32_e32 v31, v193
	v_lshl_add_u64 v[38:39], v[36:37], 0, v[30:31]
	global_load_dwordx4 v[48:51], v[20:21], off
	global_load_dwordx4 v[52:55], v[38:39], off
	global_load_dwordx4 v[56:59], v[14:15], off offset:1024
	v_mov_b32_e32 v38, v8
	v_mov_b32_e32 v39, v10
	v_pk_mul_f32 v[38:39], v[38:39], v[12:13] op_sel_hi:[1,0]
	v_mov_b32_e32 v10, v9
	v_pk_mul_f32 v[8:9], v[10:11], v[12:13] op_sel_hi:[1,0]
	s_mov_b32 s4, 0xf823d000
	v_mov_b32_e32 v33, v193
	v_mov_b32_e32 v35, v193
	s_waitcnt vmcnt(2)
	v_mov_b32_e32 v60, v48
	v_mov_b32_e32 v61, v50
	v_pk_mul_f32 v[38:39], v[38:39], v[60:61]
	s_waitcnt vmcnt(1)
	v_mov_b32_e32 v60, v52
	v_mov_b32_e32 v61, v54
	v_pk_add_f32 v[60:61], v[60:61], 1.0 op_sel_hi:[1,0]
	s_waitcnt vmcnt(0)
	v_mov_b32_e32 v62, v56
	v_mov_b32_e32 v63, v58
	v_mov_b32_e32 v50, v49
	v_mov_b32_e32 v54, v53
	v_pk_fma_f32 v[38:39], v[38:39], v[60:61], v[62:63]
	v_pk_mul_f32 v[8:9], v[8:9], v[50:51]
	v_pk_add_f32 v[10:11], v[54:55], 1.0 op_sel_hi:[1,0]
	v_mov_b32_e32 v58, v57
	v_pk_fma_f32 v[8:9], v[8:9], v[10:11], v[58:59]
	v_and_b32_sdwa v11, v38, v218 dst_sel:DWORD dst_unused:UNUSED_PAD src0_sel:WORD_1 src1_sel:DWORD
	v_add3_u32 v13, v38, v11, s80
	v_and_b32_sdwa v31, v8, v218 dst_sel:DWORD dst_unused:UNUSED_PAD src0_sel:WORD_1 src1_sel:DWORD
	v_cvt_pk_bf16_f32 v11, v39, v9
	v_add3_u32 v8, v8, v31, s80
	v_and_b32_e32 v8, 0xffff0000, v8
	v_or_b32_sdwa v10, v8, v13 dst_sel:DWORD dst_unused:UNUSED_PAD src0_sel:DWORD src1_sel:WORD_1
	v_add_co_u32_e32 v8, vcc, s4, v28
	s_nop 1
	v_addc_co_u32_e32 v9, vcc, -1, v29, vcc
	global_store_dwordx2 v[8:9], v[10:11], off offset:-3584 nt
	v_lshl_add_u64 v[10:11], v[36:37], 0, v[32:33]
	global_load_dwordx4 v[48:51], v[22:23], off
	global_load_dwordx4 v[52:55], v[10:11], off
	global_load_dwordx4 v[56:59], v[14:15], off offset:2048
	v_mov_b32_e32 v10, v4
	v_mov_b32_e32 v11, v6
	v_pk_mul_f32 v[10:11], v[10:11], v[12:13] op_sel_hi:[1,0]
	v_mov_b32_e32 v6, v5
	v_pk_mul_f32 v[4:5], v[6:7], v[12:13] op_sel_hi:[1,0]
	v_cmp_lt_i32_e32 vcc, s26, v40
	v_lshl_add_u64 v[28:29], v[28:29], 0, s[30:31]
	s_or_b64 s[2:3], vcc, s[2:3]
	s_waitcnt vmcnt(2)
	v_mov_b32_e32 v38, v48
	v_mov_b32_e32 v39, v50
	v_pk_mul_f32 v[10:11], v[10:11], v[38:39]
	s_waitcnt vmcnt(1)
	v_mov_b32_e32 v38, v52
	v_mov_b32_e32 v39, v54
	v_pk_add_f32 v[38:39], v[38:39], 1.0 op_sel_hi:[1,0]
	s_waitcnt vmcnt(0)
	v_mov_b32_e32 v60, v56
	v_mov_b32_e32 v61, v58
	v_mov_b32_e32 v50, v49
	v_mov_b32_e32 v54, v53
	v_pk_fma_f32 v[10:11], v[10:11], v[38:39], v[60:61]
	v_pk_mul_f32 v[4:5], v[4:5], v[50:51]
	v_pk_add_f32 v[6:7], v[54:55], 1.0 op_sel_hi:[1,0]
	v_mov_b32_e32 v58, v57
	v_pk_fma_f32 v[4:5], v[4:5], v[6:7], v[58:59]
	v_cvt_pk_bf16_f32 v4, v10, v4
	v_cvt_pk_bf16_f32 v5, v11, v5
	global_store_dwordx2 v[8:9], v[4:5], off offset:-3072 nt
	v_lshl_add_u64 v[10:11], v[36:37], 0, v[34:35]
	global_load_dwordx4 v[4:7], v[24:25], off
	global_load_dwordx4 v[36:39], v[10:11], off
	global_load_dwordx4 v[48:51], v[14:15], off offset:3072
	v_mov_b32_e32 v10, v0
	v_mov_b32_e32 v11, v2
	v_pk_mul_f32 v[10:11], v[10:11], v[12:13] op_sel_hi:[1,0]
	v_mov_b32_e32 v2, v1
	v_pk_mul_f32 v[0:1], v[2:3], v[12:13] op_sel_hi:[1,0]
	s_waitcnt vmcnt(2)
	v_mov_b32_e32 v14, v4
	v_mov_b32_e32 v15, v6
	v_pk_mul_f32 v[10:11], v[10:11], v[14:15]
	s_waitcnt vmcnt(1)
	v_mov_b32_e32 v15, v38
	v_mov_b32_e32 v6, v5
	v_mov_b32_e32 v38, v37
	v_mov_b32_e32 v14, v36
	s_waitcnt vmcnt(0)
	v_mov_b32_e32 v53, v50
	v_pk_mul_f32 v[0:1], v[0:1], v[6:7]
	v_pk_add_f32 v[2:3], v[38:39], 1.0 op_sel_hi:[1,0]
	v_mov_b32_e32 v50, v49
	v_pk_add_f32 v[14:15], v[14:15], 1.0 op_sel_hi:[1,0]
	v_mov_b32_e32 v52, v48
	v_pk_fma_f32 v[0:1], v[0:1], v[2:3], v[50:51]
	v_pk_fma_f32 v[10:11], v[10:11], v[14:15], v[52:53]
	v_cvt_pk_bf16_f32 v1, v11, v1
	v_cvt_pk_bf16_f32 v0, v10, v0
	global_store_dwordx2 v[8:9], v[0:1], off offset:-2560 nt
	s_andn2_b64 exec, exec, s[2:3]
	s_cbranch_execnz .LBB0_34

.LBB0_173:
	v_mov_b32_e32 v107, v193
	v_lshl_add_u64 v[28:29], v[0:1], 0, v[106:107]
	v_add_co_u32_e32 v4, vcc, 0x1000, v28
	v_min_i32_e32 v2, 0x4000, v104
	s_nop 0
	v_addc_co_u32_e32 v5, vcc, 0, v29, vcc
	v_ashrrev_i32_e32 v2, 13, v2
	v_add_co_u32_e32 v24, vcc, 0x2000, v28
	v_add_u32_e32 v2, s4, v2
	s_nop 0
	v_addc_co_u32_e32 v25, vcc, 0, v29, vcc
	v_mul_hi_i32_i24_e32 v123, 0x6000, v2
	v_mul_i32_i24_e32 v122, 0x6000, v2
	global_load_dwordx4 v[32:35], v[28:29], off nt
	global_load_dwordx4 v[16:19], v[28:29], off offset:1024 nt
	global_load_dwordx4 v[8:11], v[28:29], off offset:2048 nt
	global_load_dwordx4 v[0:3], v[28:29], off offset:3072 nt
	v_add_co_u32_e32 v28, vcc, 0x3000, v28
	v_lshlrev_b64 v[120:121], 11, v[104:105]
	s_nop 0
	v_addc_co_u32_e32 v29, vcc, 0, v29, vcc
	s_waitcnt vmcnt(4)
	v_lshl_add_u64 v[66:67], v[96:97], 0, v[120:121]
	global_load_dwordx4 v[36:39], v[4:5], off nt
	global_load_dwordx4 v[20:23], v[4:5], off offset:1024 nt
	global_load_dwordx4 v[12:15], v[4:5], off offset:2048 nt
	s_nop 0
	global_load_dwordx4 v[4:7], v[4:5], off offset:3072 nt
	s_nop 0
	global_load_dwordx4 v[60:63], v[24:25], off nt
	global_load_dwordx4 v[56:59], v[24:25], off offset:1024 nt
	global_load_dwordx4 v[40:43], v[24:25], off offset:2048 nt
	s_nop 0
	global_load_dwordx4 v[24:27], v[24:25], off offset:3072 nt
	s_nop 0
	global_load_dwordx4 v[52:55], v[28:29], off nt
	global_load_dwordx4 v[48:51], v[28:29], off offset:1024 nt
	global_load_dwordx4 v[44:47], v[28:29], off offset:2048 nt
	s_nop 0
	global_load_dwordx4 v[28:31], v[28:29], off offset:3072 nt
	s_nop 0
	global_load_dwordx2 v[72:73], v[66:67], off nt
	global_load_dwordx2 v[80:81], v[66:67], off offset:512 nt
	global_load_dwordx2 v[88:89], v[66:67], off offset:1024 nt
	global_load_dwordx2 v[126:127], v[66:67], off offset:1536 nt
	v_add_u32_e32 v66, 1, v104
	v_ashrrev_i32_e32 v67, 31, v66
	v_lshlrev_b64 v[118:119], 11, v[66:67]
	v_lshl_add_u64 v[66:67], v[96:97], 0, v[118:119]
	global_load_dwordx2 v[74:75], v[66:67], off nt
	global_load_dwordx2 v[82:83], v[66:67], off offset:512 nt
	global_load_dwordx2 v[90:91], v[66:67], off offset:1024 nt
	global_load_dwordx2 v[162:163], v[66:67], off offset:1536 nt
	v_add_u32_e32 v66, 2, v104
	v_ashrrev_i32_e32 v67, 31, v66
	v_lshlrev_b64 v[116:117], 11, v[66:67]
	v_lshl_add_u64 v[66:67], v[96:97], 0, v[116:117]
	global_load_dwordx2 v[76:77], v[66:67], off nt
	global_load_dwordx2 v[84:85], v[66:67], off offset:512 nt
	global_load_dwordx2 v[92:93], v[66:67], off offset:1024 nt
	global_load_dwordx2 v[132:133], v[66:67], off offset:1536 nt
	v_add_u32_e32 v66, 3, v104
	v_ashrrev_i32_e32 v67, 31, v66
	v_lshlrev_b64 v[114:115], 11, v[66:67]
	v_lshl_add_u64 v[66:67], v[96:97], 0, v[114:115]
	global_load_dwordx2 v[78:79], v[66:67], off nt
	global_load_dwordx2 v[86:87], v[66:67], off offset:512 nt
	global_load_dwordx2 v[178:179], v[66:67], off offset:1024 nt
	global_load_dwordx2 v[138:139], v[66:67], off offset:1536 nt
	v_lshl_add_u64 v[64:65], s[90:91], 0, v[122:123]
	v_lshl_add_u64 v[68:69], v[64:65], 0, v[106:107]
	s_mov_b64 s[0:1], 0x345a000
	v_lshl_add_u64 v[94:95], v[68:69], 0, s[0:1]
	s_mov_b32 s0, 0x345a000
	v_add_co_u32_e32 v68, vcc, s0, v68
	global_load_dwordx4 v[64:67], v[98:99], off
	s_nop 0
	v_addc_co_u32_e32 v69, vcc, 0, v69, vcc
	global_load_dwordx4 v[68:71], v[68:69], off
	s_mov_b32 s0, 0x358637bd
	s_mov_b32 s8, 0x3a800000
	s_mov_b32 s6, 0x800000
	v_mov_b32_e32 v111, v193
	v_mov_b32_e32 v113, v193
	s_add_i32 s5, s5, s93
	s_cmpk_gt_i32 s5, 0x3ff
	s_waitcnt vmcnt(17)
	v_and_b32_e32 v157, 0xffff0000, v72
	s_waitcnt vmcnt(16)
	v_and_b32_e32 v175, 0xffff0000, v80
	v_lshlrev_b32_e32 v156, 16, v72
	v_lshlrev_b32_e32 v174, 16, v80
	v_mov_b32_e32 v140, v157
	v_mov_b32_e32 v141, v175
	v_lshlrev_b32_e32 v168, 16, v73
	v_and_b32_e32 v177, 0xffff0000, v81
	v_lshlrev_b32_e32 v176, 16, v81
	v_mov_b32_e32 v80, v156
	v_mov_b32_e32 v81, v174
	v_pk_mul_f32 v[140:141], v[140:141], v[140:141]
	v_and_b32_e32 v169, 0xffff0000, v73
	s_waitcnt vmcnt(13)
	v_and_b32_e32 v165, 0xffff0000, v74
	v_pk_fma_f32 v[80:81], v[80:81], v[80:81], v[140:141]
	v_mov_b32_e32 v140, v168
	v_mov_b32_e32 v141, v176
	s_waitcnt vmcnt(12)
	v_and_b32_e32 v171, 0xffff0000, v82
	v_lshlrev_b32_e32 v164, 16, v74
	v_mov_b32_e32 v142, v169
	v_mov_b32_e32 v143, v177
	v_pk_fma_f32 v[80:81], v[140:141], v[140:141], v[80:81]
	v_lshlrev_b32_e32 v170, 16, v82
	v_and_b32_e32 v173, 0xffff0000, v83
	v_lshlrev_b32_e32 v172, 16, v83
	v_mov_b32_e32 v82, v165
	v_mov_b32_e32 v83, v171
	v_lshlrev_b32_e32 v166, 16, v75
	v_pk_fma_f32 v[188:189], v[142:143], v[142:143], v[80:81]
	v_mov_b32_e32 v80, v164
	v_mov_b32_e32 v81, v170
	v_pk_mul_f32 v[82:83], v[82:83], v[82:83]
	v_and_b32_e32 v167, 0xffff0000, v75
	s_waitcnt vmcnt(9)
	v_and_b32_e32 v137, 0xffff0000, v76
	v_pk_fma_f32 v[80:81], v[80:81], v[80:81], v[82:83]
	v_mov_b32_e32 v82, v166
	v_mov_b32_e32 v83, v172
	s_waitcnt vmcnt(8)
	v_and_b32_e32 v147, 0xffff0000, v84
	v_lshlrev_b32_e32 v136, 16, v76
	v_mov_b32_e32 v140, v167
	v_mov_b32_e32 v141, v173
	v_pk_fma_f32 v[80:81], v[82:83], v[82:83], v[80:81]
	v_lshlrev_b32_e32 v146, 16, v84
	v_mov_b32_e32 v82, v137
	v_mov_b32_e32 v83, v147
	v_lshlrev_b32_e32 v134, 16, v77
	v_pk_fma_f32 v[190:191], v[140:141], v[140:141], v[80:81]
	v_lshlrev_b32_e32 v144, 16, v85
	v_mov_b32_e32 v80, v136
	v_mov_b32_e32 v81, v146
	v_pk_mul_f32 v[82:83], v[82:83], v[82:83]
	v_and_b32_e32 v135, 0xffff0000, v77
	s_waitcnt vmcnt(5)
	v_and_b32_e32 v131, 0xffff0000, v78
	v_and_b32_e32 v145, 0xffff0000, v85
	v_pk_fma_f32 v[80:81], v[80:81], v[80:81], v[82:83]
	v_mov_b32_e32 v82, v134
	v_mov_b32_e32 v83, v144
	s_waitcnt vmcnt(4)
	v_and_b32_e32 v143, 0xffff0000, v86
	v_lshlrev_b32_e32 v130, 16, v78
	v_and_b32_e32 v129, 0xffff0000, v79
	v_lshlrev_b32_e32 v128, 16, v79
	global_load_dwordx4 v[72:75], v[98:99], off offset:1024
	global_load_dwordx4 v[76:79], v[94:95], off offset:1024
	v_mov_b32_e32 v84, v135
	v_mov_b32_e32 v85, v145
	v_pk_fma_f32 v[80:81], v[82:83], v[82:83], v[80:81]
	v_lshlrev_b32_e32 v142, 16, v86
	v_mov_b32_e32 v82, v131
	v_mov_b32_e32 v83, v143
	v_pk_fma_f32 v[158:159], v[84:85], v[84:85], v[80:81]
	v_lshlrev_b32_e32 v140, 16, v87
	v_mov_b32_e32 v80, v130
	v_mov_b32_e32 v81, v142
	v_pk_mul_f32 v[82:83], v[82:83], v[82:83]
	v_and_b32_e32 v141, 0xffff0000, v87
	v_pk_fma_f32 v[80:81], v[80:81], v[80:81], v[82:83]
	v_mov_b32_e32 v82, v128
	v_mov_b32_e32 v83, v140
	v_mov_b32_e32 v84, v129
	v_mov_b32_e32 v85, v141
	v_pk_fma_f32 v[80:81], v[82:83], v[82:83], v[80:81]
	v_and_b32_e32 v185, 0xffff0000, v88
	v_pk_fma_f32 v[160:161], v[84:85], v[84:85], v[80:81]
	global_load_dwordx4 v[80:83], v[98:99], off offset:2048
	global_load_dwordx4 v[84:87], v[94:95], off offset:2048
	v_lshlrev_b32_e32 v184, 16, v88
	v_and_b32_e32 v187, 0xffff0000, v89
	v_lshlrev_b32_e32 v186, 16, v89
	v_and_b32_e32 v181, 0xffff0000, v90
	v_lshlrev_b32_e32 v180, 16, v90
	v_and_b32_e32 v183, 0xffff0000, v91
	v_lshlrev_b32_e32 v182, 16, v91
	v_and_b32_e32 v155, 0xffff0000, v92
	v_lshlrev_b32_e32 v154, 16, v92
	v_and_b32_e32 v153, 0xffff0000, v93
	v_lshlrev_b32_e32 v152, 16, v93
	global_load_dwordx4 v[88:91], v[98:99], off offset:3072
	s_nop 0
	global_load_dwordx4 v[92:95], v[94:95], off offset:3072
	v_and_b32_e32 v205, 0xffff0000, v126
	s_waitcnt vmcnt(9)
	v_and_b32_e32 v151, 0xffff0000, v178
	v_lshlrev_b32_e32 v150, 16, v178
	v_and_b32_e32 v149, 0xffff0000, v179
	v_lshlrev_b32_e32 v148, 16, v179
	v_lshlrev_b32_e32 v204, 16, v126
	v_mov_b32_e32 v178, v185
	v_mov_b32_e32 v179, v205
	v_and_b32_e32 v225, 0xffff0000, v127
	v_lshlrev_b32_e32 v224, 16, v127
	v_mov_b32_e32 v126, v184
	v_mov_b32_e32 v127, v204
	v_pk_mul_f32 v[178:179], v[178:179], v[178:179]
	v_mov_b32_e32 v194, v187
	v_pk_fma_f32 v[126:127], v[126:127], v[126:127], v[178:179]
	v_mov_b32_e32 v178, v186
	v_mov_b32_e32 v179, v224
	v_pk_fma_f32 v[126:127], v[178:179], v[178:179], v[126:127]
	v_and_b32_e32 v179, 0xffff0000, v162
	v_mov_b32_e32 v195, v225
	v_lshlrev_b32_e32 v178, 16, v162
	v_mov_b32_e32 v232, v181
	v_mov_b32_e32 v233, v179
	v_pk_fma_f32 v[126:127], v[194:195], v[194:195], v[126:127]
	v_and_b32_e32 v195, 0xffff0000, v163
	v_lshlrev_b32_e32 v194, 16, v163
	v_mov_b32_e32 v162, v180
	v_mov_b32_e32 v163, v178
	v_pk_mul_f32 v[232:233], v[232:233], v[232:233]
	v_mov_b32_e32 v234, v183
	v_pk_fma_f32 v[162:163], v[162:163], v[162:163], v[232:233]
	v_mov_b32_e32 v232, v182
	v_mov_b32_e32 v233, v194
	v_mov_b32_e32 v235, v195
	v_pk_fma_f32 v[162:163], v[232:233], v[232:233], v[162:163]
	v_mov_b32_e32 v232, v190
	v_pk_fma_f32 v[162:163], v[234:235], v[234:235], v[162:163]
	v_mov_b32_e32 v233, v188
	v_mov_b32_e32 v188, v191
	v_pk_add_f32 v[188:189], v[232:233], v[188:189]
	v_mov_b32_e32 v190, v162
	v_mov_b32_e32 v191, v126
	v_pk_add_f32 v[188:189], v[188:189], v[190:191]
	v_mov_b32_e32 v126, v163
	v_pk_add_f32 v[126:127], v[188:189], v[126:127]
	v_mov_b32_e32 v163, v127
	v_mov_b32_e32 v162, v126
	s_nop 0
	v_add_f32_dpp v163, v163, v163 quad_perm:[1,0,3,2] row_mask:0xf bank_mask:0xf
	v_add_f32_dpp v162, v162, v162 quad_perm:[1,0,3,2] row_mask:0xf bank_mask:0xf
	s_nop 0
	v_add_f32_dpp v163, v163, v163 quad_perm:[2,3,0,1] row_mask:0xf bank_mask:0xf
	v_add_f32_dpp v162, v162, v162 quad_perm:[2,3,0,1] row_mask:0xf bank_mask:0xf
	s_nop 0
	v_add_f32_dpp v163, v163, v163 row_half_mirror row_mask:0xf bank_mask:0xf
	v_add_f32_dpp v162, v162, v162 row_half_mirror row_mask:0xf bank_mask:0xf
	s_nop 0
	v_add_f32_dpp v163, v163, v163 row_mirror row_mask:0xf bank_mask:0xf
	v_add_f32_dpp v162, v162, v162 row_mirror row_mask:0xf bank_mask:0xf
	s_nop 0
	v_mov_b32_e32 v127, v163
	v_mov_b32_e32 v126, v162
	s_nop 0
	v_permlane16_swap_b32_e32 v163, v127
	v_permlane16_swap_b32_e32 v162, v126
	s_nop 0
	v_add_f32_e32 v163, v163, v127
	v_add_f32_e32 v162, v162, v126
	s_nop 0
	v_mov_b32_e32 v127, v163
	v_mov_b32_e32 v126, v162
	s_nop 0
	v_permlane32_swap_b32_e32 v163, v127
	v_permlane32_swap_b32_e32 v162, v126
	s_nop 0
	v_add_f32_e32 v163, v163, v127
	v_add_f32_e32 v162, v162, v126
	s_nop 0
	v_mov_b64_e32 v[126:127], s[0:1]
	v_pk_fma_f32 v[162:163], v[162:163], s[8:9], v[126:127] op_sel_hi:[1,0,0]
	s_nop 0
	v_mul_f32_e32 v105, 0x4b800000, v163
	v_cmp_gt_f32_e64 s[0:1], s6, v163
	v_cmp_gt_f32_e32 vcc, s6, v162
	s_nop 0
	v_cndmask_b32_e64 v105, v163, v105, s[0:1]
	v_rsq_f32_e32 v105, v105
	s_nop 0
	v_mul_f32_e32 v109, 0x45800000, v105
	v_cndmask_b32_e64 v188, v105, v109, s[0:1]
	v_pk_mul_f32 v[156:157], v[188:189], v[156:157] op_sel_hi:[0,1]
	s_waitcnt vmcnt(7)
	v_pk_mul_f32 v[156:157], v[156:157], v[64:65]
	v_mul_f32_e32 v105, 0x4b800000, v162
	s_waitcnt vmcnt(6)
	v_pk_fma_f32 v[32:33], v[156:157], v[68:69], v[32:33]
	v_pk_mul_f32 v[156:157], v[188:189], v[168:169] op_sel_hi:[0,1]
	v_pk_mul_f32 v[156:157], v[156:157], v[66:67]
	v_cndmask_b32_e32 v105, v162, v105, vcc
	v_pk_fma_f32 v[34:35], v[156:157], v[70:71], v[34:35]
	v_pk_mul_f32 v[156:157], v[188:189], v[174:175] op_sel_hi:[0,1]
	s_waitcnt vmcnt(5)
	v_pk_mul_f32 v[156:157], v[156:157], v[72:73]
	v_rsq_f32_e32 v105, v105
	s_waitcnt vmcnt(4)
	v_pk_fma_f32 v[16:17], v[156:157], v[76:77], v[16:17]
	v_pk_mul_f32 v[156:157], v[188:189], v[176:177] op_sel_hi:[0,1]
	v_pk_mul_f32 v[156:157], v[156:157], v[74:75]
	v_mul_f32_e32 v109, 0x45800000, v105
	v_pk_fma_f32 v[18:19], v[156:157], v[78:79], v[18:19]
	v_pk_mul_f32 v[156:157], v[188:189], v[184:185] op_sel_hi:[0,1]
	s_waitcnt vmcnt(3)
	v_pk_mul_f32 v[156:157], v[156:157], v[80:81]
	v_mov_b32_e32 v168, v151
	s_waitcnt vmcnt(2)
	v_pk_fma_f32 v[8:9], v[156:157], v[84:85], v[8:9]
	v_pk_mul_f32 v[156:157], v[188:189], v[186:187] op_sel_hi:[0,1]
	v_pk_mul_f32 v[156:157], v[156:157], v[82:83]
	s_nop 0
	v_pk_fma_f32 v[10:11], v[156:157], v[86:87], v[10:11]
	v_pk_mul_f32 v[156:157], v[188:189], v[204:205] op_sel_hi:[0,1]
	s_waitcnt vmcnt(1)
	v_pk_mul_f32 v[156:157], v[156:157], v[88:89]
	s_waitcnt vmcnt(0)
	v_pk_fma_f32 v[0:1], v[156:157], v[92:93], v[0:1]
	v_pk_mul_f32 v[156:157], v[188:189], v[224:225] op_sel_hi:[0,1]
	v_pk_mul_f32 v[156:157], v[156:157], v[90:91]
	s_nop 0
	v_pk_fma_f32 v[2:3], v[156:157], v[94:95], v[2:3]
	v_cndmask_b32_e32 v156, v105, v109, vcc
	v_pk_mul_f32 v[162:163], v[156:157], v[164:165] op_sel_hi:[0,1]
	v_pk_mul_f32 v[162:163], v[162:163], v[64:65]
	v_and_b32_e32 v165, 0xffff0000, v133
	v_pk_fma_f32 v[36:37], v[162:163], v[68:69], v[36:37]
	v_pk_mul_f32 v[162:163], v[156:157], v[166:167] op_sel_hi:[0,1]
	v_pk_mul_f32 v[162:163], v[162:163], v[66:67]
	v_lshlrev_b32_e32 v164, 16, v133
	v_pk_fma_f32 v[38:39], v[162:163], v[70:71], v[38:39]
	v_pk_mul_f32 v[162:163], v[156:157], v[170:171] op_sel_hi:[0,1]
	v_pk_mul_f32 v[162:163], v[162:163], v[72:73]
	v_mov_b32_e32 v166, v153
	v_pk_fma_f32 v[20:21], v[162:163], v[76:77], v[20:21]
	v_pk_mul_f32 v[162:163], v[156:157], v[172:173] op_sel_hi:[0,1]
	v_pk_mul_f32 v[162:163], v[162:163], v[74:75]
	v_mov_b32_e32 v167, v165
	v_pk_fma_f32 v[22:23], v[162:163], v[78:79], v[22:23]
	v_pk_mul_f32 v[162:163], v[156:157], v[180:181] op_sel_hi:[0,1]
	v_pk_mul_f32 v[162:163], v[162:163], v[80:81]
	v_mov_b32_e32 v170, v149
	v_pk_fma_f32 v[12:13], v[162:163], v[84:85], v[12:13]
	v_pk_mul_f32 v[162:163], v[156:157], v[182:183] op_sel_hi:[0,1]
	v_pk_mul_f32 v[162:163], v[162:163], v[82:83]
	s_nop 0
	v_pk_fma_f32 v[14:15], v[162:163], v[86:87], v[14:15]
	v_pk_mul_f32 v[162:163], v[156:157], v[178:179] op_sel_hi:[0,1]
	v_pk_mul_f32 v[162:163], v[162:163], v[88:89]
	v_pk_mul_f32 v[156:157], v[156:157], v[194:195] op_sel_hi:[0,1]
	v_pk_fma_f32 v[4:5], v[162:163], v[92:93], v[4:5]
	v_pk_mul_f32 v[156:157], v[156:157], v[90:91]
	v_and_b32_e32 v163, 0xffff0000, v132
	v_pk_fma_f32 v[6:7], v[156:157], v[94:95], v[6:7]
	v_lshlrev_b32_e32 v162, 16, v132
	v_mov_b32_e32 v156, v155
	v_mov_b32_e32 v157, v163
	v_mov_b32_e32 v132, v154
	v_mov_b32_e32 v133, v162
	v_pk_mul_f32 v[156:157], v[156:157], v[156:157]
	s_nop 0
	v_pk_fma_f32 v[132:133], v[132:133], v[132:133], v[156:157]
	v_mov_b32_e32 v156, v152
	v_mov_b32_e32 v157, v164
	v_pk_fma_f32 v[132:133], v[156:157], v[156:157], v[132:133]
	v_and_b32_e32 v157, 0xffff0000, v138
	v_lshlrev_b32_e32 v156, 16, v138
	v_mov_b32_e32 v169, v157
	v_pk_fma_f32 v[166:167], v[166:167], v[166:167], v[132:133]
	v_and_b32_e32 v133, 0xffff0000, v139
	v_lshlrev_b32_e32 v132, 16, v139
	v_mov_b32_e32 v138, v150
	v_mov_b32_e32 v139, v156
	v_pk_mul_f32 v[168:169], v[168:169], v[168:169]
	v_mov_b32_e32 v171, v133
	v_pk_fma_f32 v[138:139], v[138:139], v[138:139], v[168:169]
	v_mov_b32_e32 v168, v148
	v_mov_b32_e32 v169, v132
	v_pk_fma_f32 v[138:139], v[168:169], v[168:169], v[138:139]
	v_mov_b32_e32 v168, v160
	v_pk_fma_f32 v[138:139], v[170:171], v[170:171], v[138:139]
	v_mov_b32_e32 v169, v158
	v_mov_b32_e32 v158, v161
	v_pk_add_f32 v[158:159], v[168:169], v[158:159]
	v_mov_b32_e32 v160, v138
	v_mov_b32_e32 v161, v166
	v_pk_add_f32 v[158:159], v[158:159], v[160:161]
	v_mov_b32_e32 v166, v139
	v_pk_add_f32 v[138:139], v[158:159], v[166:167]
	s_nop 0
	s_nop 1
	v_add_f32_dpp v139, v139, v139 quad_perm:[1,0,3,2] row_mask:0xf bank_mask:0xf
	v_add_f32_dpp v138, v138, v138 quad_perm:[1,0,3,2] row_mask:0xf bank_mask:0xf
	s_nop 0
	v_add_f32_dpp v139, v139, v139 quad_perm:[2,3,0,1] row_mask:0xf bank_mask:0xf
	v_add_f32_dpp v138, v138, v138 quad_perm:[2,3,0,1] row_mask:0xf bank_mask:0xf
	s_nop 0
	v_add_f32_dpp v139, v139, v139 row_half_mirror row_mask:0xf bank_mask:0xf
	v_add_f32_dpp v138, v138, v138 row_half_mirror row_mask:0xf bank_mask:0xf
	s_nop 0
	v_add_f32_dpp v139, v139, v139 row_mirror row_mask:0xf bank_mask:0xf
	v_add_f32_dpp v138, v138, v138 row_mirror row_mask:0xf bank_mask:0xf
	s_nop 0
	v_mov_b32_e32 v207, v139
	v_mov_b32_e32 v158, v138
	s_nop 0
	v_permlane16_swap_b32_e32 v139, v207
	v_permlane16_swap_b32_e32 v138, v158
	s_nop 0
	v_add_f32_e32 v139, v139, v207
	v_add_f32_e32 v138, v138, v158
	s_nop 0
	v_mov_b32_e32 v207, v139
	v_mov_b32_e32 v158, v138
	s_nop 0
	v_permlane32_swap_b32_e32 v139, v207
	v_permlane32_swap_b32_e32 v138, v158
	s_nop 0
	v_add_f32_e32 v139, v139, v207
	v_add_f32_e32 v138, v138, v158
	s_nop 0
	s_nop 0
	v_pk_fma_f32 v[138:139], v[138:139], s[8:9], v[126:127] op_sel_hi:[1,0,0]
	s_nop 0
	v_mul_f32_e32 v105, 0x4b800000, v139
	v_cmp_gt_f32_e64 s[0:1], s6, v139
	v_cmp_gt_f32_e32 vcc, s6, v138
	s_nop 0
	v_cndmask_b32_e64 v105, v139, v105, s[0:1]
	v_rsq_f32_e32 v105, v105
	s_nop 0
	v_mul_f32_e32 v109, 0x45800000, v105
	v_cndmask_b32_e64 v158, v105, v109, s[0:1]
	v_pk_mul_f32 v[134:135], v[158:159], v[134:135] op_sel_hi:[0,1]
	v_pk_mul_f32 v[134:135], v[66:67], v[134:135]
	v_mul_f32_e32 v105, 0x4b800000, v138
	v_pk_fma_f32 v[62:63], v[134:135], v[70:71], v[62:63]
	v_pk_mul_f32 v[134:135], v[158:159], v[146:147] op_sel_hi:[0,1]
	v_pk_mul_f32 v[134:135], v[134:135], v[72:73]
	v_cndmask_b32_e32 v105, v138, v105, vcc
	v_pk_fma_f32 v[56:57], v[134:135], v[76:77], v[56:57]
	v_pk_mul_f32 v[134:135], v[158:159], v[144:145] op_sel_hi:[0,1]
	v_pk_mul_f32 v[134:135], v[134:135], v[74:75]
	v_rsq_f32_e32 v105, v105
	v_pk_fma_f32 v[58:59], v[134:135], v[78:79], v[58:59]
	v_pk_mul_f32 v[134:135], v[158:159], v[154:155] op_sel_hi:[0,1]
	v_pk_mul_f32 v[134:135], v[134:135], v[80:81]
	v_mul_f32_e32 v109, 0x45800000, v105
	v_pk_fma_f32 v[40:41], v[134:135], v[84:85], v[40:41]
	v_pk_mul_f32 v[134:135], v[158:159], v[152:153] op_sel_hi:[0,1]
	v_pk_mul_f32 v[134:135], v[134:135], v[82:83]
	v_pk_mul_f32 v[136:137], v[158:159], v[136:137] op_sel_hi:[0,1]
	v_pk_fma_f32 v[42:43], v[134:135], v[86:87], v[42:43]
	v_pk_mul_f32 v[134:135], v[158:159], v[162:163] op_sel_hi:[0,1]
	v_pk_mul_f32 v[134:135], v[134:135], v[88:89]
	v_pk_mul_f32 v[136:137], v[64:65], v[136:137]
	v_pk_fma_f32 v[24:25], v[134:135], v[92:93], v[24:25]
	v_pk_mul_f32 v[134:135], v[158:159], v[164:165] op_sel_hi:[0,1]
	v_pk_mul_f32 v[134:135], v[134:135], v[90:91]
	s_movk_i32 s0, 0x1000
	v_pk_fma_f32 v[26:27], v[134:135], v[94:95], v[26:27]
	v_cndmask_b32_e32 v134, v105, v109, vcc
	v_pk_mul_f32 v[130:131], v[134:135], v[130:131] op_sel_hi:[0,1]
	v_pk_mul_f32 v[64:65], v[64:65], v[130:131]
	v_pk_fma_f32 v[60:61], v[68:69], v[136:137], v[60:61]
	v_pk_fma_f32 v[52:53], v[68:69], v[64:65], v[52:53]
	v_pk_mul_f32 v[64:65], v[134:135], v[128:129] op_sel_hi:[0,1]
	v_pk_mul_f32 v[64:65], v[66:67], v[64:65]
	v_mov_b32_e32 v109, v193
	v_pk_fma_f32 v[54:55], v[70:71], v[64:65], v[54:55]
	v_pk_mul_f32 v[64:65], v[134:135], v[142:143] op_sel_hi:[0,1]
	v_pk_mul_f32 v[64:65], v[72:73], v[64:65]
	v_mov_b32_e32 v70, v9
	v_pk_fma_f32 v[48:49], v[64:65], v[76:77], v[48:49]
	v_pk_mul_f32 v[64:65], v[134:135], v[140:141] op_sel_hi:[0,1]
	v_pk_mul_f32 v[64:65], v[64:65], v[74:75]
	v_mov_b32_e32 v71, v1
	v_pk_fma_f32 v[50:51], v[64:65], v[78:79], v[50:51]
	v_pk_mul_f32 v[64:65], v[134:135], v[150:151] op_sel_hi:[0,1]
	v_pk_mul_f32 v[64:65], v[64:65], v[80:81]
	v_pk_mul_f32 v[70:71], v[70:71], v[70:71]
	v_pk_fma_f32 v[44:45], v[64:65], v[84:85], v[44:45]
	v_pk_mul_f32 v[64:65], v[134:135], v[148:149] op_sel_hi:[0,1]
	v_pk_mul_f32 v[64:65], v[64:65], v[82:83]
	v_mov_b32_e32 v72, v37
	v_pk_fma_f32 v[46:47], v[64:65], v[86:87], v[46:47]
	v_pk_mul_f32 v[64:65], v[134:135], v[156:157] op_sel_hi:[0,1]
	v_pk_mul_f32 v[64:65], v[64:65], v[88:89]
	v_mov_b32_e32 v73, v21
	v_pk_fma_f32 v[28:29], v[64:65], v[92:93], v[28:29]
	v_pk_mul_f32 v[64:65], v[134:135], v[132:133] op_sel_hi:[0,1]
	v_pk_mul_f32 v[64:65], v[64:65], v[90:91]
	v_pk_mul_f32 v[72:73], v[72:73], v[72:73]
	v_pk_fma_f32 v[30:31], v[64:65], v[94:95], v[30:31]
	v_lshl_add_u64 v[64:65], v[124:125], 0, v[106:107]
	v_add_co_u32_e32 v66, vcc, s0, v64
	s_movk_i32 s0, 0x2000
	s_nop 0
	v_addc_co_u32_e32 v67, vcc, 0, v65, vcc
	v_add_co_u32_e32 v68, vcc, s0, v64
	global_store_dwordx4 v[64:65], v[32:35], off nt
	global_store_dwordx4 v[64:65], v[16:19], off offset:1024 nt
	global_store_dwordx4 v[64:65], v[8:11], off offset:2048 nt
	global_store_dwordx4 v[64:65], v[0:3], off offset:3072 nt
	v_addc_co_u32_e32 v69, vcc, 0, v65, vcc
	global_store_dwordx4 v[68:69], v[36:39], off offset:-4096 nt
	global_store_dwordx4 v[66:67], v[20:23], off offset:1024 nt
	global_store_dwordx4 v[66:67], v[12:15], off offset:2048 nt
	global_store_dwordx4 v[66:67], v[4:7], off offset:3072 nt
	global_store_dwordx4 v[68:69], v[60:63], off nt
	global_store_dwordx4 v[68:69], v[56:59], off offset:1024 nt
	global_store_dwordx4 v[68:69], v[40:43], off offset:2048 nt
	global_store_dwordx4 v[68:69], v[24:27], off offset:3072 nt
	v_mov_b32_e32 v68, v33
	v_mov_b32_e32 v69, v17
	v_mov_b32_e32 v66, v32
	v_mov_b32_e32 v67, v16
	v_pk_mul_f32 v[68:69], v[68:69], v[68:69]
	v_mov_b32_e32 v74, v13
	v_pk_fma_f32 v[66:67], v[66:67], v[66:67], v[68:69]
	v_mov_b32_e32 v68, v34
	v_mov_b32_e32 v69, v18
	v_pk_fma_f32 v[66:67], v[68:69], v[68:69], v[66:67]
	v_mov_b32_e32 v68, v35
	v_mov_b32_e32 v69, v19
	v_pk_fma_f32 v[66:67], v[68:69], v[68:69], v[66:67]
	v_mov_b32_e32 v68, v8
	v_mov_b32_e32 v69, v0
	v_pk_fma_f32 v[68:69], v[68:69], v[68:69], v[70:71]
	v_mov_b32_e32 v70, v10
	v_mov_b32_e32 v71, v2
	v_pk_fma_f32 v[68:69], v[70:71], v[70:71], v[68:69]
	v_mov_b32_e32 v70, v11
	v_mov_b32_e32 v71, v3
	v_pk_fma_f32 v[68:69], v[70:71], v[70:71], v[68:69]
	v_mov_b32_e32 v70, v36
	v_mov_b32_e32 v71, v20
	v_pk_fma_f32 v[70:71], v[70:71], v[70:71], v[72:73]
	v_mov_b32_e32 v72, v38
	v_mov_b32_e32 v73, v22
	v_pk_fma_f32 v[70:71], v[72:73], v[72:73], v[70:71]
	v_mov_b32_e32 v72, v39
	v_mov_b32_e32 v73, v23
	v_mov_b32_e32 v75, v5
	v_pk_fma_f32 v[70:71], v[72:73], v[72:73], v[70:71]
	v_mov_b32_e32 v72, v12
	v_mov_b32_e32 v73, v4
	v_pk_mul_f32 v[74:75], v[74:75], v[74:75]
	v_add_co_u32_e32 v64, vcc, s73, v64
	v_pk_fma_f32 v[72:73], v[72:73], v[72:73], v[74:75]
	v_mov_b32_e32 v74, v14
	v_mov_b32_e32 v75, v6
	v_pk_fma_f32 v[72:73], v[74:75], v[74:75], v[72:73]
	v_mov_b32_e32 v74, v15
	v_mov_b32_e32 v75, v7
	v_pk_fma_f32 v[72:73], v[74:75], v[74:75], v[72:73]
	v_mov_b32_e32 v74, v70
	v_mov_b32_e32 v75, v66
	v_mov_b32_e32 v66, v71
	v_pk_add_f32 v[66:67], v[74:75], v[66:67]
	v_mov_b32_e32 v70, v72
	v_mov_b32_e32 v71, v68
	v_pk_add_f32 v[66:67], v[66:67], v[70:71]
	v_mov_b32_e32 v68, v73
	v_pk_add_f32 v[66:67], v[66:67], v[68:69]
	v_addc_co_u32_e32 v65, vcc, 0, v65, vcc
	global_store_dwordx4 v[64:65], v[52:55], off nt
	global_store_dwordx4 v[64:65], v[48:51], off offset:1024 nt
	global_store_dwordx4 v[64:65], v[44:47], off offset:2048 nt
	global_store_dwordx4 v[64:65], v[28:31], off offset:3072 nt
	v_lshl_add_u64 v[64:65], s[96:97], 0, v[122:123]
	s_mov_b64 s[0:1], 0x3000
	v_lshl_add_u64 v[76:77], v[64:65], 0, s[0:1]
	v_mov_b32_e32 v70, v41
	v_mov_b32_e32 v71, v25
	v_pk_mul_f32 v[70:71], v[70:71], v[70:71]
	v_mov_b32_e32 v72, v53
	v_mov_b32_e32 v73, v49
	v_pk_mul_f32 v[72:73], v[72:73], v[72:73]
	v_mov_b32_e32 v74, v45
	v_mov_b32_e32 v75, v29
	v_pk_mul_f32 v[74:75], v[74:75], v[74:75]
	v_lshl_add_u64 v[86:87], v[102:103], 0, v[120:121]
	s_nop 0
	s_nop 1
	v_add_f32_dpp v67, v67, v67 quad_perm:[1,0,3,2] row_mask:0xf bank_mask:0xf
	v_add_f32_dpp v66, v66, v66 quad_perm:[1,0,3,2] row_mask:0xf bank_mask:0xf
	s_nop 0
	v_add_f32_dpp v67, v67, v67 quad_perm:[2,3,0,1] row_mask:0xf bank_mask:0xf
	v_add_f32_dpp v66, v66, v66 quad_perm:[2,3,0,1] row_mask:0xf bank_mask:0xf
	s_nop 0
	v_add_f32_dpp v67, v67, v67 row_half_mirror row_mask:0xf bank_mask:0xf
	v_add_f32_dpp v66, v66, v66 row_half_mirror row_mask:0xf bank_mask:0xf
	s_nop 0
	v_add_f32_dpp v67, v67, v67 row_mirror row_mask:0xf bank_mask:0xf
	v_add_f32_dpp v66, v66, v66 row_mirror row_mask:0xf bank_mask:0xf
	s_nop 0
	v_mov_b32_e32 v69, v67
	v_mov_b32_e32 v68, v66
	s_nop 0
	v_permlane16_swap_b32_e32 v67, v69
	v_permlane16_swap_b32_e32 v66, v68
	s_nop 0
	v_add_f32_e32 v67, v67, v69
	v_add_f32_e32 v66, v66, v68
	s_nop 0
	v_mov_b32_e32 v69, v67
	v_mov_b32_e32 v68, v66
	s_nop 0
	v_permlane32_swap_b32_e32 v67, v69
	v_permlane32_swap_b32_e32 v66, v68
	s_nop 0
	v_add_f32_e32 v67, v67, v69
	v_add_f32_e32 v66, v66, v68
	s_nop 0
	s_nop 0
	v_pk_fma_f32 v[66:67], v[66:67], s[8:9], v[126:127] op_sel_hi:[1,0,0]
	v_mov_b32_e32 v69, v57
	v_mul_f32_e32 v68, 0x4b800000, v67
	v_cmp_gt_f32_e64 s[0:1], s6, v67
	v_cmp_gt_f32_e32 vcc, s6, v66
	s_nop 0
	v_cndmask_b32_e64 v67, v67, v68, s[0:1]
	v_rsq_f32_e32 v67, v67
	s_nop 0
	v_mul_f32_e32 v68, 0x45800000, v67
	v_cndmask_b32_e64 v80, v67, v68, s[0:1]
	v_mul_f32_e32 v67, 0x4b800000, v66
	v_cndmask_b32_e32 v66, v66, v67, vcc
	v_rsq_f32_e32 v66, v66
	v_mov_b32_e32 v68, v61
	v_pk_mul_f32 v[68:69], v[68:69], v[68:69]
	v_mul_f32_e32 v67, 0x45800000, v66
	v_cndmask_b32_e32 v78, v66, v67, vcc
	v_mov_b32_e32 v66, v60
	v_mov_b32_e32 v67, v56
	v_pk_fma_f32 v[66:67], v[66:67], v[66:67], v[68:69]
	v_mov_b32_e32 v68, v62
	v_mov_b32_e32 v69, v58
	v_pk_fma_f32 v[66:67], v[68:69], v[68:69], v[66:67]
	v_mov_b32_e32 v68, v63
	v_mov_b32_e32 v69, v59
	v_pk_fma_f32 v[66:67], v[68:69], v[68:69], v[66:67]
	v_mov_b32_e32 v68, v40
	v_mov_b32_e32 v69, v24
	v_pk_fma_f32 v[68:69], v[68:69], v[68:69], v[70:71]
	v_mov_b32_e32 v70, v42
	v_mov_b32_e32 v71, v26
	v_pk_fma_f32 v[68:69], v[70:71], v[70:71], v[68:69]
	v_mov_b32_e32 v70, v43
	v_mov_b32_e32 v71, v27
	v_pk_fma_f32 v[68:69], v[70:71], v[70:71], v[68:69]
	v_mov_b32_e32 v70, v52
	v_mov_b32_e32 v71, v48
	v_pk_fma_f32 v[70:71], v[70:71], v[70:71], v[72:73]
	v_mov_b32_e32 v72, v54
	v_mov_b32_e32 v73, v50
	v_pk_fma_f32 v[70:71], v[72:73], v[72:73], v[70:71]
	v_mov_b32_e32 v72, v55
	v_mov_b32_e32 v73, v51
	v_pk_fma_f32 v[70:71], v[72:73], v[72:73], v[70:71]
	v_mov_b32_e32 v72, v44
	v_mov_b32_e32 v73, v28
	v_pk_fma_f32 v[72:73], v[72:73], v[72:73], v[74:75]
	v_mov_b32_e32 v74, v46
	v_mov_b32_e32 v75, v30
	v_pk_fma_f32 v[72:73], v[74:75], v[74:75], v[72:73]
	v_mov_b32_e32 v74, v47
	v_mov_b32_e32 v75, v31
	v_pk_fma_f32 v[72:73], v[74:75], v[74:75], v[72:73]
	v_mov_b32_e32 v74, v70
	v_mov_b32_e32 v75, v66
	v_mov_b32_e32 v66, v71
	v_pk_add_f32 v[66:67], v[74:75], v[66:67]
	v_mov_b32_e32 v70, v72
	v_mov_b32_e32 v71, v68
	v_pk_add_f32 v[66:67], v[66:67], v[70:71]
	v_mov_b32_e32 v68, v73
	v_pk_add_f32 v[66:67], v[66:67], v[68:69]
	v_lshl_add_u64 v[70:71], v[76:77], 0, v[106:107]
	s_nop 0
	s_nop 1
	v_add_f32_dpp v67, v67, v67 quad_perm:[1,0,3,2] row_mask:0xf bank_mask:0xf
	v_add_f32_dpp v66, v66, v66 quad_perm:[1,0,3,2] row_mask:0xf bank_mask:0xf
	s_nop 0
	v_add_f32_dpp v67, v67, v67 quad_perm:[2,3,0,1] row_mask:0xf bank_mask:0xf
	v_add_f32_dpp v66, v66, v66 quad_perm:[2,3,0,1] row_mask:0xf bank_mask:0xf
	s_nop 0
	v_add_f32_dpp v67, v67, v67 row_half_mirror row_mask:0xf bank_mask:0xf
	v_add_f32_dpp v66, v66, v66 row_half_mirror row_mask:0xf bank_mask:0xf
	s_nop 0
	v_add_f32_dpp v67, v67, v67 row_mirror row_mask:0xf bank_mask:0xf
	v_add_f32_dpp v66, v66, v66 row_mirror row_mask:0xf bank_mask:0xf
	s_nop 0
	v_mov_b32_e32 v69, v67
	v_mov_b32_e32 v68, v66
	s_nop 0
	v_permlane16_swap_b32_e32 v67, v69
	v_permlane16_swap_b32_e32 v66, v68
	s_nop 0
	v_add_f32_e32 v67, v67, v69
	v_add_f32_e32 v66, v66, v68
	s_nop 0
	v_mov_b32_e32 v69, v67
	v_mov_b32_e32 v68, v66
	s_nop 0
	v_permlane32_swap_b32_e32 v67, v69
	v_permlane32_swap_b32_e32 v66, v68
	s_nop 0
	v_add_f32_e32 v67, v67, v69
	v_add_f32_e32 v66, v66, v68
	s_nop 0
	s_nop 0
	v_pk_fma_f32 v[66:67], v[66:67], s[8:9], v[126:127] op_sel_hi:[1,0,0]
	s_nop 0
	v_mul_f32_e32 v68, 0x4b800000, v67
	v_cmp_gt_f32_e64 s[0:1], s6, v67
	v_cmp_gt_f32_e32 vcc, s6, v66
	s_nop 0
	v_cndmask_b32_e64 v67, v67, v68, s[0:1]
	v_rsq_f32_e32 v67, v67
	s_nop 0
	v_mul_f32_e32 v68, 0x45800000, v67
	v_cndmask_b32_e64 v84, v67, v68, s[0:1]
	v_mul_f32_e32 v67, 0x4b800000, v66
	v_cndmask_b32_e32 v66, v66, v67, vcc
	v_rsq_f32_e32 v66, v66
	s_mov_b64 s[0:1], 0x4000
	v_lshl_add_u64 v[88:89], v[64:65], 0, s[0:1]
	v_lshl_add_u64 v[68:69], v[88:89], 0, v[106:107]
	v_mul_f32_e32 v67, 0x45800000, v66
	v_cndmask_b32_e32 v82, v66, v67, vcc
	global_load_dwordx4 v[64:67], v[100:101], off
	global_load_dwordx4 v[72:75], v[68:69], off
	s_nop 0
	global_load_dwordx4 v[68:71], v[70:71], off
	v_readlane_b32 s0, v255, 7
	s_waitcnt vmcnt(2)
	v_mov_b32_e32 v93, v66
	s_waitcnt vmcnt(1)
	v_mov_b32_e32 v91, v74
	v_mov_b32_e32 v74, v73
	v_mov_b32_e32 v90, v72
	v_pk_add_f32 v[72:73], v[74:75], 1.0 op_sel_hi:[1,0]
	v_mov_b32_e32 v75, v34
	v_mov_b32_e32 v34, v33
	v_mov_b32_e32 v74, v32
	v_pk_mul_f32 v[32:33], v[34:35], v[80:81] op_sel_hi:[1,0]
	v_mov_b32_e32 v66, v65
	v_pk_mul_f32 v[74:75], v[74:75], v[80:81] op_sel_hi:[1,0]
	v_mov_b32_e32 v92, v64
	s_waitcnt vmcnt(0)
	v_mov_b32_e32 v95, v70
	v_pk_mul_f32 v[32:33], v[32:33], v[66:67]
	v_mov_b32_e32 v70, v69
	v_pk_add_f32 v[90:91], v[90:91], 1.0 op_sel_hi:[1,0]
	v_pk_mul_f32 v[74:75], v[74:75], v[92:93]
	v_mov_b32_e32 v94, v68
	v_pk_fma_f32 v[32:33], v[32:33], v[72:73], v[70:71]
	v_pk_fma_f32 v[74:75], v[74:75], v[90:91], v[94:95]
	v_cvt_pk_bf16_f32 v33, v75, v33
	v_cvt_pk_bf16_f32 v32, v74, v32
	v_mov_b32_e32 v34, v36
	v_mov_b32_e32 v35, v38
	v_pk_mul_f32 v[34:35], v[34:35], v[78:79] op_sel_hi:[1,0]
	v_mov_b32_e32 v38, v37
	v_pk_mul_f32 v[34:35], v[34:35], v[92:93]
	v_pk_mul_f32 v[36:37], v[38:39], v[78:79] op_sel_hi:[1,0]
	v_pk_fma_f32 v[34:35], v[34:35], v[90:91], v[94:95]
	v_pk_mul_f32 v[36:37], v[36:37], v[66:67]
	v_and_b32_sdwa v38, v35, v218 dst_sel:DWORD dst_unused:UNUSED_PAD src0_sel:WORD_1 src1_sel:DWORD
	v_pk_fma_f32 v[36:37], v[36:37], v[72:73], v[70:71]
	v_cvt_pk_bf16_f32 v34, v34, v36
	v_add3_u32 v35, v35, v38, s80
	v_and_b32_sdwa v38, v37, v218 dst_sel:DWORD dst_unused:UNUSED_PAD src0_sel:WORD_1 src1_sel:DWORD
	v_add3_u32 v37, v37, v38, s80
	v_and_b32_e32 v37, 0xffff0000, v37
	v_or_b32_sdwa v35, v37, v35 dst_sel:DWORD dst_unused:UNUSED_PAD src0_sel:DWORD src1_sel:WORD_1
	v_mov_b32_e32 v36, v60
	v_mov_b32_e32 v37, v62
	v_pk_mul_f32 v[36:37], v[36:37], v[84:85] op_sel_hi:[1,0]
	v_mov_b32_e32 v62, v61
	v_pk_mul_f32 v[36:37], v[92:93], v[36:37]
	v_pk_mul_f32 v[38:39], v[62:63], v[84:85] op_sel_hi:[1,0]
	v_pk_fma_f32 v[36:37], v[36:37], v[90:91], v[94:95]
	v_pk_mul_f32 v[38:39], v[66:67], v[38:39]
	v_and_b32_sdwa v60, v37, v218 dst_sel:DWORD dst_unused:UNUSED_PAD src0_sel:WORD_1 src1_sel:DWORD
	v_pk_fma_f32 v[38:39], v[38:39], v[72:73], v[70:71]
	v_cvt_pk_bf16_f32 v36, v36, v38
	v_add3_u32 v37, v37, v60, s80
	v_and_b32_sdwa v60, v39, v218 dst_sel:DWORD dst_unused:UNUSED_PAD src0_sel:WORD_1 src1_sel:DWORD
	v_add3_u32 v39, v39, v60, s80
	v_and_b32_e32 v39, 0xffff0000, v39
	v_or_b32_sdwa v37, v39, v37 dst_sel:DWORD dst_unused:UNUSED_PAD src0_sel:DWORD src1_sel:WORD_1
	v_mov_b32_e32 v38, v52
	v_mov_b32_e32 v39, v54
	v_pk_mul_f32 v[38:39], v[38:39], v[82:83] op_sel_hi:[1,0]
	v_mov_b32_e32 v54, v53
	v_pk_mul_f32 v[38:39], v[92:93], v[38:39]
	v_pk_mul_f32 v[52:53], v[54:55], v[82:83] op_sel_hi:[1,0]
	v_pk_fma_f32 v[38:39], v[90:91], v[38:39], v[94:95]
	v_pk_mul_f32 v[52:53], v[66:67], v[52:53]
	v_and_b32_sdwa v54, v39, v218 dst_sel:DWORD dst_unused:UNUSED_PAD src0_sel:WORD_1 src1_sel:DWORD
	v_pk_fma_f32 v[52:53], v[72:73], v[52:53], v[70:71]
	v_cvt_pk_bf16_f32 v38, v38, v52
	v_add3_u32 v39, v39, v54, s80
	v_and_b32_sdwa v54, v53, v218 dst_sel:DWORD dst_unused:UNUSED_PAD src0_sel:WORD_1 src1_sel:DWORD
	global_store_dwordx2 v[86:87], v[32:33], off nt
	v_lshl_add_u64 v[32:33], v[102:103], 0, v[118:119]
	v_add3_u32 v53, v53, v54, s80
	global_store_dwordx2 v[32:33], v[34:35], off nt
	v_lshl_add_u64 v[34:35], v[102:103], 0, v[116:117]
	v_and_b32_e32 v53, 0xffff0000, v53
	global_store_dwordx2 v[34:35], v[36:37], off nt
	v_lshl_add_u64 v[36:37], v[102:103], 0, v[114:115]
	v_or_b32_sdwa v39, v53, v39 dst_sel:DWORD dst_unused:UNUSED_PAD src0_sel:DWORD src1_sel:WORD_1
	global_store_dwordx2 v[36:37], v[38:39], off nt
	v_lshl_add_u64 v[64:65], v[76:77], 0, v[108:109]
	v_lshl_add_u64 v[38:39], v[88:89], 0, v[108:109]
	global_load_dwordx4 v[52:55], v[100:101], off offset:1024
	global_load_dwordx4 v[60:63], v[38:39], off
	s_nop 0
	global_load_dwordx4 v[64:67], v[64:65], off
	v_add_u32_e32 v104, s0, v104
	s_waitcnt vmcnt(2)
	v_mov_b32_e32 v69, v54
	s_waitcnt vmcnt(1)
	v_mov_b32_e32 v39, v62
	v_mov_b32_e32 v62, v61
	v_mov_b32_e32 v38, v60
	v_pk_add_f32 v[60:61], v[62:63], 1.0 op_sel_hi:[1,0]
	v_mov_b32_e32 v63, v18
	v_mov_b32_e32 v18, v17
	v_mov_b32_e32 v62, v16
	v_pk_mul_f32 v[16:17], v[18:19], v[80:81] op_sel_hi:[1,0]
	v_mov_b32_e32 v54, v53
	v_pk_mul_f32 v[62:63], v[62:63], v[80:81] op_sel_hi:[1,0]
	v_mov_b32_e32 v68, v52
	s_waitcnt vmcnt(0)
	v_mov_b32_e32 v71, v66
	v_pk_mul_f32 v[16:17], v[16:17], v[54:55]
	v_mov_b32_e32 v66, v65
	v_pk_add_f32 v[38:39], v[38:39], 1.0 op_sel_hi:[1,0]
	v_pk_mul_f32 v[62:63], v[62:63], v[68:69]
	v_mov_b32_e32 v70, v64
	v_pk_fma_f32 v[16:17], v[16:17], v[60:61], v[66:67]
	v_pk_fma_f32 v[62:63], v[62:63], v[38:39], v[70:71]
	v_cvt_pk_bf16_f32 v17, v63, v17
	v_cvt_pk_bf16_f32 v16, v62, v16
	global_store_dwordx2 v[86:87], v[16:17], off offset:512 nt
	v_mov_b32_e32 v16, v20
	v_mov_b32_e32 v17, v22
	v_pk_mul_f32 v[16:17], v[16:17], v[78:79] op_sel_hi:[1,0]
	v_mov_b32_e32 v22, v21
	v_pk_mul_f32 v[16:17], v[16:17], v[68:69]
	v_pk_mul_f32 v[18:19], v[22:23], v[78:79] op_sel_hi:[1,0]
	v_pk_fma_f32 v[16:17], v[16:17], v[38:39], v[70:71]
	v_pk_mul_f32 v[18:19], v[18:19], v[54:55]
	v_and_b32_sdwa v20, v17, v218 dst_sel:DWORD dst_unused:UNUSED_PAD src0_sel:WORD_1 src1_sel:DWORD
	v_pk_fma_f32 v[18:19], v[18:19], v[60:61], v[66:67]
	v_cvt_pk_bf16_f32 v16, v16, v18
	v_add3_u32 v17, v17, v20, s80
	v_and_b32_sdwa v20, v19, v218 dst_sel:DWORD dst_unused:UNUSED_PAD src0_sel:WORD_1 src1_sel:DWORD
	v_add3_u32 v19, v19, v20, s80
	v_and_b32_e32 v19, 0xffff0000, v19
	v_or_b32_sdwa v17, v19, v17 dst_sel:DWORD dst_unused:UNUSED_PAD src0_sel:DWORD src1_sel:WORD_1
	global_store_dwordx2 v[32:33], v[16:17], off offset:512 nt
	v_mov_b32_e32 v16, v56
	v_mov_b32_e32 v17, v58
	v_pk_mul_f32 v[16:17], v[16:17], v[84:85] op_sel_hi:[1,0]
	v_mov_b32_e32 v58, v57
	v_pk_mul_f32 v[16:17], v[16:17], v[68:69]
	v_pk_mul_f32 v[18:19], v[58:59], v[84:85] op_sel_hi:[1,0]
	v_pk_fma_f32 v[16:17], v[16:17], v[38:39], v[70:71]
	v_pk_mul_f32 v[18:19], v[18:19], v[54:55]
	v_and_b32_sdwa v20, v17, v218 dst_sel:DWORD dst_unused:UNUSED_PAD src0_sel:WORD_1 src1_sel:DWORD
	v_pk_fma_f32 v[18:19], v[18:19], v[60:61], v[66:67]
	v_cvt_pk_bf16_f32 v16, v16, v18
	v_add3_u32 v17, v17, v20, s80
	v_and_b32_sdwa v20, v19, v218 dst_sel:DWORD dst_unused:UNUSED_PAD src0_sel:WORD_1 src1_sel:DWORD
	v_add3_u32 v19, v19, v20, s80
	v_and_b32_e32 v19, 0xffff0000, v19
	v_or_b32_sdwa v17, v19, v17 dst_sel:DWORD dst_unused:UNUSED_PAD src0_sel:DWORD src1_sel:WORD_1
	global_store_dwordx2 v[34:35], v[16:17], off offset:512 nt
	v_mov_b32_e32 v16, v48
	v_mov_b32_e32 v17, v50
	v_pk_mul_f32 v[16:17], v[16:17], v[82:83] op_sel_hi:[1,0]
	v_mov_b32_e32 v50, v49
	v_pk_mul_f32 v[16:17], v[16:17], v[68:69]
	v_pk_mul_f32 v[18:19], v[50:51], v[82:83] op_sel_hi:[1,0]
	v_pk_fma_f32 v[16:17], v[16:17], v[38:39], v[70:71]
	v_pk_mul_f32 v[18:19], v[18:19], v[54:55]
	v_and_b32_sdwa v20, v17, v218 dst_sel:DWORD dst_unused:UNUSED_PAD src0_sel:WORD_1 src1_sel:DWORD
	v_pk_fma_f32 v[18:19], v[18:19], v[60:61], v[66:67]
	v_cvt_pk_bf16_f32 v16, v16, v18
	v_add3_u32 v17, v17, v20, s80
	v_and_b32_sdwa v20, v19, v218 dst_sel:DWORD dst_unused:UNUSED_PAD src0_sel:WORD_1 src1_sel:DWORD
	v_add3_u32 v19, v19, v20, s80
	v_and_b32_e32 v19, 0xffff0000, v19
	v_or_b32_sdwa v17, v19, v17 dst_sel:DWORD dst_unused:UNUSED_PAD src0_sel:DWORD src1_sel:WORD_1
	global_store_dwordx2 v[36:37], v[16:17], off offset:512 nt
	v_lshl_add_u64 v[20:21], v[88:89], 0, v[110:111]
	v_lshl_add_u64 v[38:39], v[76:77], 0, v[110:111]
	global_load_dwordx4 v[16:19], v[100:101], off offset:2048
	s_nop 0
	global_load_dwordx4 v[20:23], v[20:21], off
	s_nop 0
	global_load_dwordx4 v[48:51], v[38:39], off
	s_waitcnt vmcnt(2)
	v_mov_b32_e32 v53, v18
	s_waitcnt vmcnt(1)
	v_mov_b32_e32 v39, v22
	v_mov_b32_e32 v22, v21
	v_mov_b32_e32 v38, v20
	v_pk_add_f32 v[20:21], v[22:23], 1.0 op_sel_hi:[1,0]
	v_mov_b32_e32 v23, v10
	v_mov_b32_e32 v10, v9
	v_mov_b32_e32 v22, v8
	v_pk_mul_f32 v[8:9], v[10:11], v[80:81] op_sel_hi:[1,0]
	v_mov_b32_e32 v18, v17
	v_pk_mul_f32 v[22:23], v[22:23], v[80:81] op_sel_hi:[1,0]
	v_mov_b32_e32 v52, v16
	s_waitcnt vmcnt(0)
	v_mov_b32_e32 v55, v50
	v_pk_mul_f32 v[8:9], v[8:9], v[18:19]
	v_mov_b32_e32 v50, v49
	v_pk_add_f32 v[38:39], v[38:39], 1.0 op_sel_hi:[1,0]
	v_pk_mul_f32 v[22:23], v[22:23], v[52:53]
	v_mov_b32_e32 v54, v48
	v_pk_fma_f32 v[8:9], v[8:9], v[20:21], v[50:51]
	v_pk_fma_f32 v[22:23], v[22:23], v[38:39], v[54:55]
	v_cvt_pk_bf16_f32 v9, v23, v9
	v_cvt_pk_bf16_f32 v8, v22, v8
	global_store_dwordx2 v[86:87], v[8:9], off offset:1024 nt
	v_mov_b32_e32 v8, v12
	v_mov_b32_e32 v9, v14
	v_pk_mul_f32 v[8:9], v[8:9], v[78:79] op_sel_hi:[1,0]
	v_mov_b32_e32 v14, v13
	v_pk_mul_f32 v[8:9], v[8:9], v[52:53]
	v_pk_mul_f32 v[10:11], v[14:15], v[78:79] op_sel_hi:[1,0]
	v_pk_fma_f32 v[8:9], v[8:9], v[38:39], v[54:55]
	v_pk_mul_f32 v[10:11], v[10:11], v[18:19]
	v_and_b32_sdwa v12, v9, v218 dst_sel:DWORD dst_unused:UNUSED_PAD src0_sel:WORD_1 src1_sel:DWORD
	v_pk_fma_f32 v[10:11], v[10:11], v[20:21], v[50:51]
	v_cvt_pk_bf16_f32 v8, v8, v10
	v_add3_u32 v9, v9, v12, s80
	v_and_b32_sdwa v12, v11, v218 dst_sel:DWORD dst_unused:UNUSED_PAD src0_sel:WORD_1 src1_sel:DWORD
	v_add3_u32 v11, v11, v12, s80
	v_and_b32_e32 v11, 0xffff0000, v11
	v_or_b32_sdwa v9, v11, v9 dst_sel:DWORD dst_unused:UNUSED_PAD src0_sel:DWORD src1_sel:WORD_1
	global_store_dwordx2 v[32:33], v[8:9], off offset:1024 nt
	v_mov_b32_e32 v8, v40
	v_mov_b32_e32 v9, v42
	v_pk_mul_f32 v[8:9], v[8:9], v[84:85] op_sel_hi:[1,0]
	v_mov_b32_e32 v42, v41
	v_pk_mul_f32 v[8:9], v[8:9], v[52:53]
	v_pk_mul_f32 v[10:11], v[42:43], v[84:85] op_sel_hi:[1,0]
	v_pk_fma_f32 v[8:9], v[8:9], v[38:39], v[54:55]
	v_pk_mul_f32 v[10:11], v[10:11], v[18:19]
	v_and_b32_sdwa v12, v9, v218 dst_sel:DWORD dst_unused:UNUSED_PAD src0_sel:WORD_1 src1_sel:DWORD
	v_pk_fma_f32 v[10:11], v[10:11], v[20:21], v[50:51]
	v_cvt_pk_bf16_f32 v8, v8, v10
	v_add3_u32 v9, v9, v12, s80
	v_and_b32_sdwa v12, v11, v218 dst_sel:DWORD dst_unused:UNUSED_PAD src0_sel:WORD_1 src1_sel:DWORD
	v_add3_u32 v11, v11, v12, s80
	v_and_b32_e32 v11, 0xffff0000, v11
	v_or_b32_sdwa v9, v11, v9 dst_sel:DWORD dst_unused:UNUSED_PAD src0_sel:DWORD src1_sel:WORD_1
	global_store_dwordx2 v[34:35], v[8:9], off offset:1024 nt
	v_mov_b32_e32 v8, v44
	v_mov_b32_e32 v9, v46
	v_pk_mul_f32 v[8:9], v[8:9], v[82:83] op_sel_hi:[1,0]
	v_mov_b32_e32 v46, v45
	v_pk_mul_f32 v[8:9], v[8:9], v[52:53]
	v_pk_mul_f32 v[10:11], v[46:47], v[82:83] op_sel_hi:[1,0]
	v_pk_fma_f32 v[8:9], v[8:9], v[38:39], v[54:55]
	v_pk_mul_f32 v[10:11], v[10:11], v[18:19]
	v_and_b32_sdwa v12, v9, v218 dst_sel:DWORD dst_unused:UNUSED_PAD src0_sel:WORD_1 src1_sel:DWORD
	v_pk_fma_f32 v[10:11], v[10:11], v[20:21], v[50:51]
	v_cvt_pk_bf16_f32 v8, v8, v10
	v_add3_u32 v9, v9, v12, s80
	v_and_b32_sdwa v12, v11, v218 dst_sel:DWORD dst_unused:UNUSED_PAD src0_sel:WORD_1 src1_sel:DWORD
	v_add3_u32 v11, v11, v12, s80
	v_and_b32_e32 v11, 0xffff0000, v11
	v_or_b32_sdwa v9, v11, v9 dst_sel:DWORD dst_unused:UNUSED_PAD src0_sel:DWORD src1_sel:WORD_1
	global_store_dwordx2 v[36:37], v[8:9], off offset:1024 nt
	v_lshl_add_u64 v[12:13], v[88:89], 0, v[112:113]
	v_lshl_add_u64 v[16:17], v[76:77], 0, v[112:113]
	global_load_dwordx4 v[8:11], v[100:101], off offset:3072
	s_nop 0
	global_load_dwordx4 v[12:15], v[12:13], off
	s_nop 0
	global_load_dwordx4 v[16:19], v[16:17], off
	s_waitcnt vmcnt(2)
	v_mov_b32_e32 v23, v10
	s_waitcnt vmcnt(1)
	v_mov_b32_e32 v21, v14
	v_mov_b32_e32 v14, v13
	v_mov_b32_e32 v20, v12
	v_pk_add_f32 v[12:13], v[14:15], 1.0 op_sel_hi:[1,0]
	v_mov_b32_e32 v15, v2
	v_mov_b32_e32 v2, v1
	v_mov_b32_e32 v14, v0
	v_pk_mul_f32 v[0:1], v[2:3], v[80:81] op_sel_hi:[1,0]
	v_mov_b32_e32 v10, v9
	v_pk_mul_f32 v[14:15], v[14:15], v[80:81] op_sel_hi:[1,0]
	v_mov_b32_e32 v22, v8
	s_waitcnt vmcnt(0)
	v_mov_b32_e32 v39, v18
	v_pk_mul_f32 v[0:1], v[0:1], v[10:11]
	v_mov_b32_e32 v18, v17
	v_pk_add_f32 v[20:21], v[20:21], 1.0 op_sel_hi:[1,0]
	v_pk_mul_f32 v[14:15], v[14:15], v[22:23]
	v_mov_b32_e32 v38, v16
	v_pk_fma_f32 v[0:1], v[0:1], v[12:13], v[18:19]
	v_pk_fma_f32 v[14:15], v[14:15], v[20:21], v[38:39]
	v_cvt_pk_bf16_f32 v1, v15, v1
	v_cvt_pk_bf16_f32 v0, v14, v0
	global_store_dwordx2 v[86:87], v[0:1], off offset:1536 nt
	v_mov_b32_e32 v0, v4
	v_mov_b32_e32 v1, v6
	v_pk_mul_f32 v[0:1], v[0:1], v[78:79] op_sel_hi:[1,0]
	v_mov_b32_e32 v6, v5
	v_pk_mul_f32 v[0:1], v[0:1], v[22:23]
	v_pk_mul_f32 v[2:3], v[6:7], v[78:79] op_sel_hi:[1,0]
	v_pk_fma_f32 v[0:1], v[0:1], v[20:21], v[38:39]
	v_pk_mul_f32 v[2:3], v[2:3], v[10:11]
	v_and_b32_sdwa v4, v1, v218 dst_sel:DWORD dst_unused:UNUSED_PAD src0_sel:WORD_1 src1_sel:DWORD
	v_pk_fma_f32 v[2:3], v[2:3], v[12:13], v[18:19]
	v_cvt_pk_bf16_f32 v0, v0, v2
	v_add3_u32 v1, v1, v4, s80
	v_and_b32_sdwa v4, v3, v218 dst_sel:DWORD dst_unused:UNUSED_PAD src0_sel:WORD_1 src1_sel:DWORD
	v_add3_u32 v3, v3, v4, s80
	v_and_b32_e32 v3, 0xffff0000, v3
	v_or_b32_sdwa v1, v3, v1 dst_sel:DWORD dst_unused:UNUSED_PAD src0_sel:DWORD src1_sel:WORD_1
	global_store_dwordx2 v[32:33], v[0:1], off offset:1536 nt
	v_mov_b32_e32 v0, v24
	v_mov_b32_e32 v1, v26
	v_pk_mul_f32 v[0:1], v[0:1], v[84:85] op_sel_hi:[1,0]
	v_mov_b32_e32 v26, v25
	v_pk_mul_f32 v[0:1], v[0:1], v[22:23]
	v_pk_mul_f32 v[2:3], v[26:27], v[84:85] op_sel_hi:[1,0]
	v_pk_fma_f32 v[0:1], v[0:1], v[20:21], v[38:39]
	v_pk_mul_f32 v[2:3], v[2:3], v[10:11]
	v_and_b32_sdwa v4, v1, v218 dst_sel:DWORD dst_unused:UNUSED_PAD src0_sel:WORD_1 src1_sel:DWORD
	v_pk_fma_f32 v[2:3], v[2:3], v[12:13], v[18:19]
	v_cvt_pk_bf16_f32 v0, v0, v2
	v_add3_u32 v1, v1, v4, s80
	v_and_b32_sdwa v4, v3, v218 dst_sel:DWORD dst_unused:UNUSED_PAD src0_sel:WORD_1 src1_sel:DWORD
	v_add3_u32 v3, v3, v4, s80
	v_and_b32_e32 v3, 0xffff0000, v3
	v_or_b32_sdwa v1, v3, v1 dst_sel:DWORD dst_unused:UNUSED_PAD src0_sel:DWORD src1_sel:WORD_1
	global_store_dwordx2 v[34:35], v[0:1], off offset:1536 nt
	v_mov_b32_e32 v0, v28
	v_mov_b32_e32 v1, v30
	v_pk_mul_f32 v[0:1], v[0:1], v[82:83] op_sel_hi:[1,0]
	v_mov_b32_e32 v30, v29
	v_pk_mul_f32 v[0:1], v[0:1], v[22:23]
	v_pk_mul_f32 v[2:3], v[30:31], v[82:83] op_sel_hi:[1,0]
	v_pk_fma_f32 v[0:1], v[0:1], v[20:21], v[38:39]
	v_pk_mul_f32 v[2:3], v[2:3], v[10:11]
	v_and_b32_sdwa v4, v1, v218 dst_sel:DWORD dst_unused:UNUSED_PAD src0_sel:WORD_1 src1_sel:DWORD
	v_pk_fma_f32 v[2:3], v[2:3], v[12:13], v[18:19]
	v_cvt_pk_bf16_f32 v0, v0, v2
	v_add3_u32 v1, v1, v4, s80
	v_and_b32_sdwa v4, v3, v218 dst_sel:DWORD dst_unused:UNUSED_PAD src0_sel:WORD_1 src1_sel:DWORD
	v_add3_u32 v3, v3, v4, s80
	v_and_b32_e32 v3, 0xffff0000, v3
	v_or_b32_sdwa v1, v3, v1 dst_sel:DWORD dst_unused:UNUSED_PAD src0_sel:DWORD src1_sel:WORD_1
	global_store_dwordx2 v[36:37], v[0:1], off offset:1536 nt
	s_cbranch_scc1 .LBB0_179

.LBB0_182:
	v_min_i32_e32 v2, 0x4000, v16
	v_ashrrev_i32_e32 v2, 13, v2
	v_mov_b32_e32 v53, v193
	v_lshlrev_b64 v[60:61], 11, v[16:17]
	v_add_u32_e32 v2, s8, v2
	v_lshl_add_u64 v[0:1], v[0:1], 0, v[52:53]
	v_lshl_add_u64 v[16:17], v[44:45], 0, v[60:61]
	v_mul_hi_i32_i24_e32 v63, 0x6000, v2
	v_mul_i32_i24_e32 v62, 0x6000, v2
	global_load_dwordx4 v[12:15], v[0:1], off nt
	global_load_dwordx4 v[8:11], v[0:1], off offset:1024 nt
	global_load_dwordx4 v[4:7], v[0:1], off offset:2048 nt
	s_nop 0
	global_load_dwordx4 v[0:3], v[0:1], off offset:3072 nt
	s_nop 0
	global_load_dwordx2 v[24:25], v[16:17], off nt
	global_load_dwordx2 v[32:33], v[16:17], off offset:512 nt
	global_load_dwordx2 v[40:41], v[16:17], off offset:1024 nt
	global_load_dwordx2 v[76:77], v[16:17], off offset:1536 nt
	v_lshl_add_u64 v[18:19], s[90:91], 0, v[62:63]
	v_lshl_add_u64 v[20:21], v[18:19], 0, v[52:53]
	s_mov_b64 s[0:1], 0x345a000
	v_lshl_add_u64 v[84:85], v[20:21], 0, s[0:1]
	s_mov_b32 s0, 0x345a000
	v_add_co_u32_e32 v20, vcc, s0, v20
	global_load_dwordx4 v[16:19], v[46:47], off
	s_nop 0
	v_addc_co_u32_e32 v21, vcc, 0, v21, vcc
	global_load_dwordx4 v[20:23], v[20:21], off
	s_mov_b32 s0, 0x800000
	s_mov_b64 s[10:11], 0x3000
	v_mov_b32_e32 v59, v193
	s_waitcnt vmcnt(5)
	v_and_b32_e32 v67, 0xffff0000, v24
	s_waitcnt vmcnt(4)
	v_and_b32_e32 v69, 0xffff0000, v32
	v_lshlrev_b32_e32 v66, 16, v24
	v_lshlrev_b32_e32 v68, 16, v32
	v_mov_b32_e32 v34, v67
	v_mov_b32_e32 v35, v69
	v_lshlrev_b32_e32 v70, 16, v25
	v_and_b32_e32 v73, 0xffff0000, v33
	v_lshlrev_b32_e32 v72, 16, v33
	v_mov_b32_e32 v32, v66
	v_mov_b32_e32 v33, v68
	v_pk_mul_f32 v[34:35], v[34:35], v[34:35]
	v_and_b32_e32 v71, 0xffff0000, v25
	global_load_dwordx4 v[28:31], v[46:47], off offset:1024
	global_load_dwordx4 v[24:27], v[84:85], off offset:1024
	v_pk_fma_f32 v[32:33], v[32:33], v[32:33], v[34:35]
	v_mov_b32_e32 v34, v70
	v_mov_b32_e32 v35, v72
	v_mov_b32_e32 v36, v71
	v_mov_b32_e32 v37, v73
	v_pk_fma_f32 v[32:33], v[34:35], v[34:35], v[32:33]
	s_waitcnt vmcnt(5)
	v_and_b32_e32 v75, 0xffff0000, v40
	v_pk_fma_f32 v[78:79], v[36:37], v[36:37], v[32:33]
	global_load_dwordx4 v[36:39], v[46:47], off offset:2048
	global_load_dwordx4 v[32:35], v[84:85], off offset:2048
	v_lshlrev_b32_e32 v74, 16, v40
	v_and_b32_e32 v83, 0xffff0000, v41
	v_lshlrev_b32_e32 v82, 16, v41
	global_load_dwordx4 v[40:43], v[46:47], off offset:3072
	global_load_dwordx4 v[92:95], v[84:85], off offset:3072
	s_waitcnt vmcnt(8)
	v_and_b32_e32 v81, 0xffff0000, v76
	v_lshlrev_b32_e32 v80, 16, v76
	v_mov_b32_e32 v96, v75
	v_mov_b32_e32 v97, v81
	v_and_b32_e32 v85, 0xffff0000, v77
	v_lshlrev_b32_e32 v84, 16, v77
	v_mov_b32_e32 v76, v74
	v_mov_b32_e32 v77, v80
	v_pk_mul_f32 v[96:97], v[96:97], v[96:97]
	v_mov_b32_e32 v98, v83
	v_pk_fma_f32 v[76:77], v[76:77], v[76:77], v[96:97]
	v_mov_b32_e32 v96, v82
	v_mov_b32_e32 v97, v84
	v_mov_b32_e32 v99, v85
	v_pk_fma_f32 v[76:77], v[96:97], v[96:97], v[76:77]
	v_add_f32_e32 v55, v78, v79
	v_pk_fma_f32 v[76:77], v[98:99], v[98:99], v[76:77]
	s_nop 0
	v_add_f32_e32 v55, v55, v76
	v_add_f32_e32 v55, v55, v77
	s_nop 0
	s_nop 1
	v_add_f32_dpp v55, v55, v55 quad_perm:[1,0,3,2] row_mask:0xf bank_mask:0xf
	s_nop 1
	v_add_f32_dpp v55, v55, v55 quad_perm:[2,3,0,1] row_mask:0xf bank_mask:0xf
	s_nop 1
	v_add_f32_dpp v55, v55, v55 row_half_mirror row_mask:0xf bank_mask:0xf
	s_nop 1
	v_add_f32_dpp v55, v55, v55 row_mirror row_mask:0xf bank_mask:0xf
	s_nop 1
	v_mov_b32_e32 v57, v55
	s_nop 1
	v_permlane16_swap_b32_e32 v55, v57
	s_nop 1
	v_add_f32_e32 v55, v55, v57
	s_nop 1
	v_mov_b32_e32 v57, v55
	s_nop 1
	v_permlane32_swap_b32_e32 v55, v57
	s_nop 1
	v_add_f32_e32 v55, v55, v57
	s_nop 1
	v_fmamk_f32 v55, v55, 0x3a800000, v219
	v_cmp_gt_f32_e32 vcc, s0, v55
	v_mul_f32_e32 v57, 0x4b800000, v55
	s_nop 0
	v_cndmask_b32_e32 v55, v55, v57, vcc
	v_rsq_f32_e32 v55, v55
	s_nop 0
	v_mul_f32_e32 v57, 0x45800000, v55
	v_cndmask_b32_e32 v76, v55, v57, vcc
	v_pk_mul_f32 v[66:67], v[76:77], v[66:67] op_sel_hi:[0,1]
	s_waitcnt vmcnt(7)
	v_pk_mul_f32 v[16:17], v[16:17], v[66:67]
	v_pk_mul_f32 v[66:67], v[76:77], v[70:71] op_sel_hi:[0,1]
	s_waitcnt vmcnt(6)
	v_pk_fma_f32 v[12:13], v[20:21], v[16:17], v[12:13]
	v_pk_mul_f32 v[16:17], v[76:77], v[68:69] op_sel_hi:[0,1]
	v_pk_mul_f32 v[18:19], v[18:19], v[66:67]
	s_waitcnt vmcnt(5)
	v_pk_mul_f32 v[16:17], v[28:29], v[16:17]
	v_pk_fma_f32 v[14:15], v[22:23], v[18:19], v[14:15]
	v_pk_mul_f32 v[18:19], v[76:77], v[72:73] op_sel_hi:[0,1]
	s_waitcnt vmcnt(4)
	v_pk_fma_f32 v[8:9], v[24:25], v[16:17], v[8:9]
	v_pk_mul_f32 v[16:17], v[76:77], v[74:75] op_sel_hi:[0,1]
	v_pk_mul_f32 v[18:19], v[30:31], v[18:19]
	s_waitcnt vmcnt(3)
	v_pk_mul_f32 v[16:17], v[16:17], v[36:37]
	v_pk_fma_f32 v[10:11], v[26:27], v[18:19], v[10:11]
	v_pk_mul_f32 v[18:19], v[76:77], v[82:83] op_sel_hi:[0,1]
	s_waitcnt vmcnt(2)
	v_pk_fma_f32 v[4:5], v[16:17], v[32:33], v[4:5]
	v_pk_mul_f32 v[16:17], v[76:77], v[80:81] op_sel_hi:[0,1]
	v_mov_b32_e32 v22, v13
	v_mov_b32_e32 v23, v9
	v_pk_mul_f32 v[18:19], v[18:19], v[38:39]
	s_waitcnt vmcnt(1)
	v_pk_mul_f32 v[16:17], v[16:17], v[40:41]
	v_mov_b32_e32 v20, v12
	v_mov_b32_e32 v21, v8
	v_pk_mul_f32 v[22:23], v[22:23], v[22:23]
	v_pk_fma_f32 v[6:7], v[18:19], v[34:35], v[6:7]
	v_pk_mul_f32 v[18:19], v[76:77], v[84:85] op_sel_hi:[0,1]
	s_waitcnt vmcnt(0)
	v_pk_fma_f32 v[0:1], v[16:17], v[92:93], v[0:1]
	v_pk_fma_f32 v[20:21], v[20:21], v[20:21], v[22:23]
	v_mov_b32_e32 v22, v14
	v_mov_b32_e32 v23, v10
	v_pk_mul_f32 v[18:19], v[18:19], v[42:43]
	v_pk_fma_f32 v[20:21], v[22:23], v[22:23], v[20:21]
	v_mov_b32_e32 v22, v15
	v_mov_b32_e32 v23, v11
	v_mov_b32_e32 v24, v5
	v_mov_b32_e32 v25, v1
	v_pk_fma_f32 v[2:3], v[18:19], v[94:95], v[2:3]
	v_pk_fma_f32 v[20:21], v[22:23], v[22:23], v[20:21]
	v_mov_b32_e32 v22, v4
	v_mov_b32_e32 v23, v0
	v_pk_mul_f32 v[24:25], v[24:25], v[24:25]
	v_lshl_add_u64 v[16:17], v[64:65], 0, v[52:53]
	v_pk_fma_f32 v[22:23], v[22:23], v[22:23], v[24:25]
	v_mov_b32_e32 v24, v6
	v_mov_b32_e32 v25, v2
	v_pk_fma_f32 v[22:23], v[24:25], v[24:25], v[22:23]
	v_mov_b32_e32 v24, v7
	v_mov_b32_e32 v25, v3
	v_pk_fma_f32 v[22:23], v[24:25], v[24:25], v[22:23]
	v_add_f32_e32 v20, v20, v21
	global_store_dwordx4 v[16:17], v[12:15], off nt
	global_store_dwordx4 v[16:17], v[8:11], off offset:1024 nt
	global_store_dwordx4 v[16:17], v[4:7], off offset:2048 nt
	global_store_dwordx4 v[16:17], v[0:3], off offset:3072 nt
	v_lshl_add_u64 v[16:17], s[96:97], 0, v[62:63]
	v_add_f32_e32 v20, v20, v22
	v_lshl_add_u64 v[18:19], v[16:17], 0, s[10:11]
	v_add_f32_e32 v22, v20, v23
	s_mov_b64 s[10:11], 0x4000
	v_lshl_add_u64 v[20:21], v[16:17], 0, s[10:11]
	ds_bpermute_b32 v16, v86, v22
	v_lshl_add_u64 v[26:27], v[20:21], 0, v[52:53]
	v_lshl_add_u64 v[30:31], v[18:19], 0, v[52:53]
	v_mov_b32_e32 v34, v12
	v_mov_b32_e32 v35, v14
	s_waitcnt lgkmcnt(0)
	v_add_f32_e32 v16, v22, v16
	global_load_dwordx4 v[22:25], v[48:49], off
	s_nop 0
	global_load_dwordx4 v[26:29], v[26:27], off
	s_nop 0
	global_load_dwordx4 v[30:33], v[30:31], off
	ds_bpermute_b32 v17, v87, v16
	v_mov_b32_e32 v14, v13
	v_mov_b32_e32 v55, v193
	v_mov_b32_e32 v57, v193
	s_waitcnt lgkmcnt(0)
	v_add_f32_e32 v16, v16, v17
	ds_bpermute_b32 v17, v88, v16
	s_waitcnt lgkmcnt(0)
	v_add_f32_e32 v16, v16, v17
	ds_bpermute_b32 v17, v89, v16
	s_waitcnt lgkmcnt(0)
	v_add_f32_e32 v16, v16, v17
	ds_bpermute_b32 v17, v90, v16
	s_waitcnt lgkmcnt(0)
	v_add_f32_e32 v16, v16, v17
	ds_bpermute_b32 v17, v91, v16
	s_waitcnt lgkmcnt(0)
	v_add_f32_e32 v16, v16, v17
	v_fmamk_f32 v16, v16, 0x3a800000, v219
	v_cmp_gt_f32_e32 vcc, s0, v16
	v_mul_f32_e32 v17, 0x4b800000, v16
	v_readlane_b32 s0, v255, 11
	v_cndmask_b32_e32 v16, v16, v17, vcc
	v_rsq_f32_e32 v16, v16
	v_add_u32_e32 v192, s0, v192
	s_movk_i32 s0, 0x1ff
	v_readlane_b32 s1, v255, 12
	v_mul_f32_e32 v17, 0x45800000, v16
	v_cndmask_b32_e32 v16, v16, v17, vcc
	v_pk_mul_f32 v[34:35], v[34:35], v[16:17] op_sel_hi:[1,0]
	v_pk_mul_f32 v[12:13], v[14:15], v[16:17] op_sel_hi:[1,0]
	v_cmp_lt_i32_e32 vcc, s0, v192
	s_or_b64 s[6:7], vcc, s[6:7]
	s_waitcnt vmcnt(2)
	v_mov_b32_e32 v36, v22
	v_mov_b32_e32 v37, v24
	v_pk_mul_f32 v[34:35], v[36:37], v[34:35]
	s_waitcnt vmcnt(1)
	v_mov_b32_e32 v36, v26
	v_mov_b32_e32 v37, v28
	v_pk_add_f32 v[36:37], v[36:37], 1.0 op_sel_hi:[1,0]
	s_waitcnt vmcnt(0)
	v_mov_b32_e32 v38, v30
	v_mov_b32_e32 v39, v32
	v_mov_b32_e32 v24, v23
	v_mov_b32_e32 v28, v27
	v_pk_fma_f32 v[34:35], v[36:37], v[34:35], v[38:39]
	v_pk_mul_f32 v[12:13], v[24:25], v[12:13]
	v_pk_add_f32 v[14:15], v[28:29], 1.0 op_sel_hi:[1,0]
	v_mov_b32_e32 v32, v31
	v_pk_fma_f32 v[12:13], v[14:15], v[12:13], v[32:33]
	v_and_b32_sdwa v15, v34, v218 dst_sel:DWORD dst_unused:UNUSED_PAD src0_sel:WORD_1 src1_sel:DWORD
	v_add3_u32 v17, v34, v15, s80
	v_and_b32_sdwa v22, v12, v218 dst_sel:DWORD dst_unused:UNUSED_PAD src0_sel:WORD_1 src1_sel:DWORD
	v_cvt_pk_bf16_f32 v15, v35, v13
	v_add3_u32 v12, v12, v22, s80
	v_and_b32_e32 v12, 0xffff0000, v12
	v_or_b32_sdwa v14, v12, v17 dst_sel:DWORD dst_unused:UNUSED_PAD src0_sel:DWORD src1_sel:WORD_1
	v_lshl_add_u64 v[12:13], v[50:51], 0, v[60:61]
	global_store_dwordx2 v[12:13], v[14:15], off nt
	v_lshl_add_u64 v[30:31], v[18:19], 0, v[54:55]
	v_lshl_add_u64 v[14:15], v[20:21], 0, v[54:55]
	global_load_dwordx4 v[22:25], v[48:49], off offset:1024
	global_load_dwordx4 v[26:29], v[14:15], off
	s_nop 0
	global_load_dwordx4 v[30:33], v[30:31], off
	v_mov_b32_e32 v14, v8
	v_mov_b32_e32 v15, v10
	v_pk_mul_f32 v[14:15], v[14:15], v[16:17] op_sel_hi:[1,0]
	v_mov_b32_e32 v10, v9
	v_pk_mul_f32 v[8:9], v[10:11], v[16:17] op_sel_hi:[1,0]
	s_waitcnt vmcnt(2)
	v_mov_b32_e32 v34, v22
	v_mov_b32_e32 v35, v24
	v_pk_mul_f32 v[14:15], v[14:15], v[34:35]
	s_waitcnt vmcnt(1)
	v_mov_b32_e32 v34, v26
	v_mov_b32_e32 v35, v28
	v_pk_add_f32 v[34:35], v[34:35], 1.0 op_sel_hi:[1,0]
	s_waitcnt vmcnt(0)
	v_mov_b32_e32 v36, v30
	v_mov_b32_e32 v37, v32
	v_mov_b32_e32 v24, v23
	v_mov_b32_e32 v28, v27
	v_pk_fma_f32 v[14:15], v[14:15], v[34:35], v[36:37]
	v_pk_mul_f32 v[8:9], v[8:9], v[24:25]
	v_pk_add_f32 v[10:11], v[28:29], 1.0 op_sel_hi:[1,0]
	v_mov_b32_e32 v32, v31
	v_pk_fma_f32 v[8:9], v[8:9], v[10:11], v[32:33]
	v_cvt_pk_bf16_f32 v8, v14, v8
	v_cvt_pk_bf16_f32 v9, v15, v9
	global_store_dwordx2 v[12:13], v[8:9], off offset:512 nt
	v_lshl_add_u64 v[26:27], v[18:19], 0, v[56:57]
	v_lshl_add_u64 v[14:15], v[20:21], 0, v[56:57]
	global_load_dwordx4 v[8:11], v[48:49], off offset:2048
	global_load_dwordx4 v[22:25], v[14:15], off
	s_nop 0
	global_load_dwordx4 v[26:29], v[26:27], off
	v_mov_b32_e32 v14, v4
	v_mov_b32_e32 v15, v6
	v_pk_mul_f32 v[14:15], v[14:15], v[16:17] op_sel_hi:[1,0]
	v_mov_b32_e32 v6, v5
	v_pk_mul_f32 v[4:5], v[6:7], v[16:17] op_sel_hi:[1,0]
	s_waitcnt vmcnt(2)
	v_mov_b32_e32 v30, v8
	v_mov_b32_e32 v31, v10
	v_pk_mul_f32 v[14:15], v[14:15], v[30:31]
	s_waitcnt vmcnt(1)
	v_mov_b32_e32 v31, v24
	v_mov_b32_e32 v10, v9
	v_mov_b32_e32 v24, v23
	v_mov_b32_e32 v30, v22
	s_waitcnt vmcnt(0)
	v_mov_b32_e32 v33, v28
	v_pk_mul_f32 v[4:5], v[4:5], v[10:11]
	v_pk_add_f32 v[6:7], v[24:25], 1.0 op_sel_hi:[1,0]
	v_mov_b32_e32 v28, v27
	v_pk_add_f32 v[30:31], v[30:31], 1.0 op_sel_hi:[1,0]
	v_mov_b32_e32 v32, v26
	v_pk_fma_f32 v[4:5], v[4:5], v[6:7], v[28:29]
	v_pk_fma_f32 v[14:15], v[14:15], v[30:31], v[32:33]
	v_cvt_pk_bf16_f32 v5, v15, v5
	v_cvt_pk_bf16_f32 v4, v14, v4
	global_store_dwordx2 v[12:13], v[4:5], off offset:1024 nt
	v_lshl_add_u64 v[8:9], v[20:21], 0, v[58:59]
	v_lshl_add_u64 v[14:15], v[18:19], 0, v[58:59]
	global_load_dwordx4 v[4:7], v[48:49], off offset:3072
	s_nop 0
	global_load_dwordx4 v[8:11], v[8:9], off
	s_nop 0
	global_load_dwordx4 v[18:21], v[14:15], off
	v_mov_b32_e32 v14, v0
	v_mov_b32_e32 v15, v2
	v_pk_mul_f32 v[14:15], v[14:15], v[16:17] op_sel_hi:[1,0]
	v_mov_b32_e32 v2, v1
	v_pk_mul_f32 v[0:1], v[2:3], v[16:17] op_sel_hi:[1,0]
	s_waitcnt vmcnt(2)
	v_mov_b32_e32 v22, v4
	v_mov_b32_e32 v23, v6
	v_pk_mul_f32 v[14:15], v[14:15], v[22:23]
	s_waitcnt vmcnt(1)
	v_mov_b32_e32 v23, v10
	v_mov_b32_e32 v6, v5
	v_mov_b32_e32 v10, v9
	v_mov_b32_e32 v22, v8
	s_waitcnt vmcnt(0)
	v_mov_b32_e32 v25, v20
	v_pk_mul_f32 v[0:1], v[0:1], v[6:7]
	v_pk_add_f32 v[2:3], v[10:11], 1.0 op_sel_hi:[1,0]
	v_mov_b32_e32 v20, v19
	v_pk_add_f32 v[22:23], v[22:23], 1.0 op_sel_hi:[1,0]
	v_mov_b32_e32 v24, v18
	v_pk_fma_f32 v[0:1], v[0:1], v[2:3], v[20:21]
	v_pk_fma_f32 v[14:15], v[14:15], v[22:23], v[24:25]
	v_cvt_pk_bf16_f32 v1, v15, v1
	v_cvt_pk_bf16_f32 v0, v14, v0
	global_store_dwordx2 v[12:13], v[0:1], off offset:1536 nt
	s_andn2_b64 exec, exec, s[6:7]
	s_cbranch_execz .LBB0_188
